# P2 pre-stage: 27 late loads hoisted to the top with their address slices (one exposed latency instead of ~8) + job0 tap-load de-serialization
# speedup vs baseline: 1.0132x; 1.0001x over previous
; #define LAS __attribute__((address_space(3)))
; __device__ __forceinline__ float bflo(unsigned w) { return __uint_as_float(w << 16); }
; __device__ __forceinline__ float bfhi(unsigned w) { return __uint_as_float(w & 0xffff0000u); }
; __device__ __forceinline__ void conv8(const bf16* row, int p0, float c0, float c1, float c2, float cb, float (&o)[8]) {
;     const v4u w = *(const v4u*)(row + p0);
;     float x[10];
;     x[0] = bf1(row[p0 > 0 ? p0 - 1 : 0]) * (p0 > 0 ? 1.f : 0.f); x[9] = bf1(row[p0 + 8 < SEQL ? p0 + 8 : SEQL - 1]) * (p0 + 8 < SEQL ? 1.f : 0.f);
;     x[1] = bflo(w.x); x[2] = bfhi(w.x); x[3] = bflo(w.y); x[4] = bfhi(w.y); x[5] = bflo(w.z); x[6] = bfhi(w.z); x[7] = bflo(w.w); x[8] = bfhi(w.w);
; #pragma unroll
;     for (int e = 0; e < 8; ++e) o[e] = c0 * x[e] + c1 * x[e + 1] + c2 * x[e + 2] + cb;
; }
; template <int VAR> __device__ __forceinline__ void hyena_conv_phase(const Frame& F, const bf16* ZT, const bf16* GT, const float* conv_w, const float* conv_b, const float* skip, float* gscr, float* zscr, bf16* UT) {
;     ...
;     for (int c = F.bid; c < DM; c += F.G) {
;         const bf16* rx0 = ZT + (size_t)c * MTOK; const bf16* rx1 = ZT + (size_t)(DM + c) * MTOK; const bf16* rv = ZT + (size_t)(2 * DM + c) * MTOK;
;         const float a0 = conv_w[c], a1 = conv_w[3072 + c], a2 = conv_w[6144 + c], ab = conv_b[c];
;         const float b0 = conv_w[DM + c], b1 = conv_w[3072 + DM + c], b2 = conv_w[6144 + DM + c], bb = conv_b[DM + c];
;         const float v0 = conv_w[2 * DM + c], v1 = conv_w[3072 + 2 * DM + c], v2 = conv_w[6144 + 2 * DM + c], vb = conv_b[2 * DM + c];
;         const bf16* gf = GT + (size_t)c * SEQL; const bf16* gb = GT + (size_t)(DM + c) * SEQL;
;         int t = t0; asm volatile("" : "+v"(t));
;         float gsc = 1.f; const float skn = skip[c] * (1.0f / 32768.0f);
; #pragma unroll
;         for (int qi = 0; qi < 8; ++qi) { const int q = t + 512 * qi; const int b = qi >> 2, p0 = (q & 2047) * 8; float cv[8], cx[8];
;             conv8(rv + b * SEQL, p0, v0, v1, v2, vb, cv); conv8(rx1 + b * SEQL, p0, b0, b1, b2, bb, cx);
;             f32x4 o0, o1;
; #pragma unroll
;             for (int e = 0; e < 4; ++e) { o0[e] = cv[e] * cx[e]; o1[e] = cv[4 + e] * cx[4 + e]; }
;             *(LAS f32x4*)(X + b * SEQL + p0) = o0; *(LAS f32x4*)(X + b * SEQL + p0 + 4) = o1; }
.LBB0_323:
	s_add_i32 s6, s80, 0x400
	s_ashr_i32 s81, s80, 31
	s_ashr_i32 s7, s6, 31
	s_lshl_b64 s[82:83], s[80:81], 15
	s_lshl_b64 s[20:21], s[6:7], 16
	s_add_u32 s90, s40, s20
	s_addc_u32 s91, s41, s21
	s_lshl_b64 s[20:21], s[80:81], 16
	s_add_u32 s10, s40, s20
	s_addc_u32 s20, s41, s21
	s_add_u32 s92, s10, 0x8000000
	s_addc_u32 s93, s20, 0
	s_lshl_b64 s[76:77], s[80:81], 2
	s_add_u32 s88, s48, s76
	s_addc_u32 s89, s49, s77
	s_add_u32 s94, s50, s76
	s_addc_u32 s95, s51, s77
	global_load_dword v19, v152, s[88:89]
	global_load_dword v18, v153, s[88:89]
	global_load_dword v24, v154, s[88:89]
	global_load_dword v16, v154, s[94:95]
	global_load_dword v20, v17, s[88:89]
	global_load_dword v193, v17, s[94:95]
	global_load_dword v31, v158, s[88:89]
	global_load_dword v28, v159, s[88:89]
	global_load_dword v25, v155, s[88:89]
	global_load_dword v26, v156, s[88:89]
	global_load_dword v30, v157, s[88:89]
	global_load_dword v32, v157, s[94:95]
	s_lshl_b64 s[88:89], s[6:7], 15
	v_mov_b32_e32 v22, v221
	s_add_u32 s6, s14, s76
	v_lshlrev_b32_e32 v27, 3, v22
	s_addc_u32 s7, s15, s77
	v_and_b32_e32 v29, 0x3ff8, v27
	v_lshlrev_b32_e32 v23, 1, v29
	s_add_u32 s94, s10, 0x8008000
	v_sub_u32_e64 v8, v29, 1 clamp
	global_load_dwordx4 v[0:3], v23, s[92:93]
	global_load_dwordx4 v[4:7], v23, s[90:91]
	s_addc_u32 s95, s20, 0
	v_lshlrev_b32_e32 v8, 1, v8
	v_min_u32_e32 v9, 0x3ff7, v29
	s_add_u32 s96, s90, 0x8000
	v_lshlrev_b32_e32 v9, 1, v9
	s_addc_u32 s97, s91, 0
	global_load_ushort v47, v8, s[92:93]
	global_load_ushort v49, v9, s[92:93] offset:16
	global_load_ushort v37, v8, s[94:95]
	global_load_ushort v33, v8, s[96:97]
	global_load_ushort v39, v9, s[94:95] offset:16
	global_load_ushort v38, v9, s[96:97] offset:16
	global_load_ushort v52, v9, s[90:91] offset:16
	global_load_ushort v56, v8, s[90:91]
	global_load_dword v21, v17, s[6:7]
	v_add_u32_e32 v8, 0x1000, v27
	v_and_b32_e32 v78, 0x3ff8, v8
	v_lshlrev_b32_e32 v35, 1, v78
	v_sub_u32_e64 v8, v78, 1 clamp
	v_min_u32_e32 v9, 0x3ff7, v78
	v_lshlrev_b32_e32 v34, 1, v8
	v_lshlrev_b32_e32 v36, 1, v9
	global_load_dwordx4 v[12:15], v35, s[92:93]
	global_load_dwordx4 v[8:11], v35, s[90:91]
	global_load_ushort v68, v34, s[92:93]
	global_load_ushort v69, v36, s[92:93] offset:16
	global_load_ushort v42, v36, s[94:95] offset:16
	global_load_ushort v43, v36, s[96:97] offset:16
	global_load_ushort v70, v36, s[90:91] offset:16
	global_load_ushort v45, v34, s[94:95]
	global_load_ushort v44, v34, s[96:97]
	global_load_ushort v71, v34, s[90:91]
	v_bitop3_b32 v218, v27, s87, v160 bitop3:0x6c
	v_sub_u32_e64 v219, v218, 1 clamp
	v_lshlrev_b32_e32 v230, 1, v219
	global_load_ushort v86, v230, s[92:93]
	v_bitop3_b32 v218, v27, s87, v160 bitop3:0x6c
	v_lshlrev_b32_e32 v219, 1, v218
	global_load_dwordx4 v[134:137], v219, s[92:93]
	v_bitop3_b32 v218, v27, s87, v160 bitop3:0x6c
	v_min_u32_e32 v219, 0x3ff7, v218
	v_lshlrev_b32_e32 v230, 1, v219
	global_load_ushort v88, v230, s[92:93] offset:16
	v_bitop3_b32 v218, v27, s87, v160 bitop3:0x6c
	v_min_u32_e32 v219, 0x3ff7, v218
	v_lshlrev_b32_e32 v230, 1, v219
	global_load_ushort v90, v230, s[94:95] offset:16
	v_bitop3_b32 v218, v27, s87, v160 bitop3:0x6c
	v_min_u32_e32 v219, 0x3ff7, v218
	v_lshlrev_b32_e32 v230, 1, v219
	global_load_ushort v92, v230, s[96:97] offset:16
	v_bitop3_b32 v218, v27, s87, v160 bitop3:0x6c
	v_min_u32_e32 v219, 0x3ff7, v218
	v_lshlrev_b32_e32 v230, 1, v219
	global_load_ushort v94, v230, s[90:91] offset:16
	v_bitop3_b32 v218, v27, s87, v160 bitop3:0x6c
	v_sub_u32_e64 v219, v218, 1 clamp
	v_lshlrev_b32_e32 v230, 1, v219
	global_load_ushort v96, v230, s[94:95]
	v_bitop3_b32 v218, v27, s87, v160 bitop3:0x6c
	v_sub_u32_e64 v219, v218, 1 clamp
	v_lshlrev_b32_e32 v230, 1, v219
	global_load_ushort v98, v230, s[96:97]
	v_bitop3_b32 v218, v27, s87, v160 bitop3:0x6c
	v_sub_u32_e64 v219, v218, 1 clamp
	v_lshlrev_b32_e32 v230, 1, v219
	global_load_ushort v100, v230, s[90:91]
	v_bitop3_b32 v218, v27, s87, v160 bitop3:0x6c
	v_lshlrev_b32_e32 v219, 1, v218
	global_load_dwordx4 v[138:141], v219, s[90:91]
	v_add_u32_e32 v218, 0x3000, v27
	v_and_b32_e32 v219, 0x3ff8, v218
	v_sub_u32_e64 v230, v219, 1 clamp
	v_lshlrev_b32_e32 v232, 1, v230
	global_load_ushort v102, v232, s[92:93]
	v_add_u32_e32 v218, 0x3000, v27
	v_and_b32_e32 v219, 0x3ff8, v218
	v_lshlrev_b32_e32 v230, 1, v219
	global_load_dwordx4 v[142:145], v230, s[92:93]
	v_add_u32_e32 v218, 0x3000, v27
	v_and_b32_e32 v219, 0x3ff8, v218
	v_min_u32_e32 v230, 0x3ff7, v219
	v_lshlrev_b32_e32 v232, 1, v230
	global_load_ushort v104, v232, s[92:93] offset:16
	v_add_u32_e32 v218, 0x3000, v27
	v_and_b32_e32 v219, 0x3ff8, v218
	v_min_u32_e32 v230, 0x3ff7, v219
	v_lshlrev_b32_e32 v232, 1, v230
	global_load_ushort v106, v232, s[94:95] offset:16
	v_add_u32_e32 v218, 0x3000, v27
	v_and_b32_e32 v219, 0x3ff8, v218
	v_min_u32_e32 v230, 0x3ff7, v219
	v_lshlrev_b32_e32 v232, 1, v230
	global_load_ushort v108, v232, s[96:97] offset:16
	v_add_u32_e32 v218, 0x3000, v27
	v_and_b32_e32 v219, 0x3ff8, v218
	v_min_u32_e32 v230, 0x3ff7, v219
	v_lshlrev_b32_e32 v232, 1, v230
	global_load_ushort v110, v232, s[90:91] offset:16
	v_add_u32_e32 v218, 0x3000, v27
	v_and_b32_e32 v219, 0x3ff8, v218
	v_sub_u32_e64 v230, v219, 1 clamp
	v_lshlrev_b32_e32 v232, 1, v230
	global_load_ushort v112, v232, s[94:95]
	v_add_u32_e32 v218, 0x3000, v27
	v_and_b32_e32 v219, 0x3ff8, v218
	v_sub_u32_e64 v230, v219, 1 clamp
	v_lshlrev_b32_e32 v232, 1, v230
	global_load_ushort v114, v232, s[96:97]
	v_add_u32_e32 v218, 0x3000, v27
	v_and_b32_e32 v219, 0x3ff8, v218
	v_sub_u32_e64 v230, v219, 1 clamp
	v_lshlrev_b32_e32 v232, 1, v230
	global_load_ushort v116, v232, s[90:91]
	v_add_u32_e32 v218, 0x3000, v27
	v_and_b32_e32 v219, 0x3ff8, v218
	v_lshlrev_b32_e32 v230, 1, v219
	global_load_dwordx4 v[146:149], v230, s[90:91]
	global_load_dwordx4 v[212:215], v23, s[94:95]
	global_load_dwordx4 v[222:225], v23, s[96:97]
	global_load_dwordx4 v[226:229], v35, s[94:95]
	global_load_dwordx4 v[236:239], v35, s[96:97]
	v_bitop3_b32 v218, v27, s87, v160 bitop3:0x6c
	v_lshlrev_b32_e32 v219, 1, v218
	global_load_dwordx4 v[240:243], v219, s[94:95]
	v_bitop3_b32 v218, v27, s87, v160 bitop3:0x6c
	v_lshlrev_b32_e32 v219, 1, v218
	global_load_dwordx4 v[244:247], v219, s[96:97]
	v_add_u32_e32 v218, 0x3000, v27
	v_and_b32_e32 v219, 0x3ff8, v218
	v_lshlrev_b32_e32 v230, 1, v219
	global_load_dwordx4 v[250:253], v230, s[94:95]
	v_cmp_eq_u32_e32 vcc, 0, v29
	v_bitop3_b32 v79, v27, s87, v160 bitop3:0x6c
	s_add_u32 s88, s16, s88
	v_cndmask_b32_e64 v40, 1.0, 0, vcc
	v_cmp_eq_u32_e32 vcc, s11, v29
	s_addc_u32 s89, s17, s89
	v_mov_b32_e32 v210, 1.0
	v_cndmask_b32_e64 v41, 1.0, 0, vcc
	v_cmp_eq_u32_e32 vcc, 0, v78
	s_mov_b32 s81, 0
	s_waitcnt vmcnt(47)
; #define LAS __attribute__((address_space(3)))
; __device__ __forceinline__ float bflo(unsigned w) { return __uint_as_float(w << 16); }
; __device__ __forceinline__ float bfhi(unsigned w) { return __uint_as_float(w & 0xffff0000u); }
; __device__ __forceinline__ float bf1(bf16 h) { return __uint_as_float((unsigned)h << 16); }
; __device__ __forceinline__ void conv8(const bf16* row, int p0, float c0, float c1, float c2, float cb, float (&o)[8]) {
;     const v4u w = *(const v4u*)(row + p0);
;     float x[10];
;     x[0] = bf1(row[p0 > 0 ? p0 - 1 : 0]) * (p0 > 0 ? 1.f : 0.f); x[9] = bf1(row[p0 + 8 < SEQL ? p0 + 8 : SEQL - 1]) * (p0 + 8 < SEQL ? 1.f : 0.f);
;     x[1] = bflo(w.x); x[2] = bfhi(w.x); x[3] = bflo(w.y); x[4] = bfhi(w.y); x[5] = bflo(w.z); x[6] = bfhi(w.z); x[7] = bflo(w.w); x[8] = bfhi(w.w);
; #pragma unroll
;     for (int e = 0; e < 8; ++e) o[e] = c0 * x[e] + c1 * x[e + 1] + c2 * x[e + 2] + cb;
; }
; template <int VAR> __device__ __forceinline__ void hyena_conv_phase(const Frame& F, const bf16* ZT, const bf16* GT, const float* conv_w, const float* conv_b, const float* skip, float* gscr, float* zscr, bf16* UT) {
;     ...
; #pragma unroll
;         for (int qi = 0; qi < 8; ++qi) { const int q = t + 512 * qi; const int b = qi >> 2, p0 = (q & 2047) * 8; float cv[8], cx[8];
;             conv8(rv + b * SEQL, p0, v0, v1, v2, vb, cv); conv8(rx1 + b * SEQL, p0, b0, b1, b2, bb, cx);
;             f32x4 o0, o1;
; #pragma unroll
;             for (int e = 0; e < 4; ++e) { o0[e] = cv[e] * cx[e]; o1[e] = cv[4 + e] * cx[4 + e]; }
;             *(LAS f32x4*)(X + b * SEQL + p0) = o0; *(LAS f32x4*)(X + b * SEQL + p0 + 4) = o1; }
	v_lshlrev_b32_e32 v34, 16, v0
	v_and_b32_e32 v51, s0, v1
	v_and_b32_e32 v50, 0xffff0000, v0
	v_lshlrev_b32_e32 v53, 16, v1
	s_waitcnt vmcnt(46)
	v_and_b32_e32 v55, s0, v5
	v_and_b32_e32 v54, 0xffff0000, v4
	v_lshlrev_b32_e32 v57, 16, v5
	s_waitcnt vmcnt(45)
	v_lshlrev_b32_e32 v0, 16, v47
	s_waitcnt vmcnt(39)
	v_pk_mov_b32 v[50:51], v[52:53], v[50:51] op_sel:[1,0]
	s_waitcnt vmcnt(38)
	v_pk_mov_b32 v[54:55], v[56:57], v[54:55] op_sel:[1,0]
	v_mul_f32_e32 v58, v40, v0
	v_lshlrev_b32_e32 v0, 16, v56
	v_mov_b32_e32 v59, v51
	v_mov_b32_e32 v61, v55
	v_mul_f32_e32 v60, v40, v0
	v_lshlrev_b32_e32 v36, 16, v4
	v_pk_mul_f32 v[58:59], v[30:31], v[58:59]
	v_pk_mul_f32 v[60:61], v[24:25], v[60:61]
	v_pk_fma_f32 v[58:59], v[30:31], v[34:35], v[58:59] op_sel:[0,0,1] op_sel_hi:[1,0,0]
	v_pk_fma_f32 v[60:61], v[24:25], v[36:37], v[60:61] op_sel:[0,0,1] op_sel_hi:[1,0,0]
	v_pk_fma_f32 v[58:59], v[28:29], v[50:51], v[58:59] op_sel_hi:[0,1,1]
	v_pk_fma_f32 v[60:61], v[26:27], v[54:55], v[60:61] op_sel_hi:[0,1,1]
	v_lshlrev_b32_e32 v4, 16, v49
	v_pk_add_f32 v[58:59], v[32:33], v[58:59] op_sel_hi:[0,1]
	v_pk_add_f32 v[60:61], v[16:17], v[60:61] op_sel_hi:[0,1]
	v_and_b32_e32 v46, 0xffff0000, v3
	v_mul_f32_e32 v47, v41, v4
	v_lshlrev_b32_e32 v4, 16, v52
	v_pk_mul_f32 v[58:59], v[58:59], v[60:61]
	v_and_b32_e32 v61, 16, v2
	v_and_b32_e32 v60, 0xffff0000, v1
	v_lshlrev_b32_e32 v1, 16, v2
	v_and_b32_e32 v63, 16, v3
	v_and_b32_e32 v62, 0xffff0000, v2
	v_lshlrev_b32_e32 v65, 16, v3
	v_and_b32_e32 v3, 16, v6
	v_and_b32_e32 v2, 0xffff0000, v5
	v_mul_f32_e32 v49, v41, v4
	v_mov_b32_e32 v34, v31
	v_mov_b32_e32 v4, v2
	v_mov_b32_e32 v36, v25
	v_pk_mul_f32 v[50:51], v[30:31], v[50:51] op_sel_hi:[0,1]
	v_pk_mul_f32 v[54:55], v[24:25], v[54:55] op_sel_hi:[0,1]
	v_pk_mov_b32 v[52:53], v[52:53], v[60:61] op_sel:[1,0]
	v_pk_mov_b32 v[2:3], v[56:57], v[2:3] op_sel:[1,0]
	v_mov_b32_e32 v0, v60
	v_lshlrev_b32_e32 v5, 16, v6
	v_pk_fma_f32 v[50:51], v[34:35], v[52:53], v[50:51] op_sel:[0,0,1] op_sel_hi:[0,1,0]
	v_pk_fma_f32 v[2:3], v[36:37], v[2:3], v[54:55] op_sel:[0,0,1] op_sel_hi:[0,1,0]
	v_pk_fma_f32 v[50:51], v[28:29], v[0:1], v[50:51] op_sel_hi:[0,1,1]
	v_pk_fma_f32 v[2:3], v[26:27], v[4:5], v[2:3] op_sel_hi:[0,1,1]
	v_pk_add_f32 v[50:51], v[32:33], v[50:51] op_sel_hi:[0,1]
	v_pk_add_f32 v[2:3], v[16:17], v[2:3] op_sel_hi:[0,1]
	v_pk_mul_f32 v[2:3], v[50:51], v[2:3]
	v_mov_b32_e32 v50, v65
	v_mov_b32_e32 v51, v46
	v_and_b32_e32 v48, 0xffff0000, v7
	v_mov_b32_e32 v64, v62
	v_and_b32_e32 v67, 16, v7
	v_and_b32_e32 v66, 0xffff0000, v6
	v_lshlrev_b32_e32 v7, 16, v7
	v_pk_mul_f32 v[50:51], v[34:35], v[50:51] op_sel_hi:[0,1]
	v_pk_mov_b32 v[62:63], v[0:1], v[62:63] op_sel:[1,0]
	v_mov_b32_e32 v6, v66
	v_pk_mov_b32 v[66:67], v[4:5], v[66:67] op_sel:[1,0]
	v_mov_b32_e32 v52, v7
	v_mov_b32_e32 v53, v48
	v_pk_fma_f32 v[50:51], v[30:31], v[64:65], v[50:51] op_sel_hi:[0,1,1]
	v_pk_mul_f32 v[54:55], v[34:35], v[62:63] op_sel_hi:[0,1]
	v_pk_fma_f32 v[46:47], v[28:29], v[46:47], v[50:51] op_sel_hi:[0,1,1]
	v_pk_mul_f32 v[50:51], v[36:37], v[66:67] op_sel_hi:[0,1]
	v_pk_mul_f32 v[52:53], v[36:37], v[52:53] op_sel_hi:[0,1]
	v_pk_fma_f32 v[0:1], v[30:31], v[0:1], v[54:55] op_sel_hi:[0,1,1]
	v_pk_fma_f32 v[52:53], v[24:25], v[6:7], v[52:53] op_sel_hi:[0,1,1]
	v_pk_fma_f32 v[4:5], v[24:25], v[4:5], v[50:51] op_sel_hi:[0,1,1]
	v_pk_fma_f32 v[0:1], v[28:29], v[64:65], v[0:1] op_sel_hi:[0,1,1]
	v_pk_fma_f32 v[4:5], v[26:27], v[6:7], v[4:5] op_sel_hi:[0,1,1]
	v_pk_fma_f32 v[6:7], v[26:27], v[48:49], v[52:53] op_sel_hi:[0,1,1]
	v_pk_add_f32 v[46:47], v[32:33], v[46:47] op_sel_hi:[0,1]
	v_pk_add_f32 v[0:1], v[32:33], v[0:1] op_sel_hi:[0,1]
	v_pk_add_f32 v[6:7], v[16:17], v[6:7] op_sel_hi:[0,1]
	v_pk_add_f32 v[4:5], v[16:17], v[4:5] op_sel_hi:[0,1]
	v_lshlrev_b32_e32 v48, 2, v29
	v_pk_mul_f32 v[4:5], v[0:1], v[4:5]
	v_pk_mul_f32 v[6:7], v[46:47], v[6:7]
	v_add_u32_e32 v46, 0, v48
	v_mov_b32_e32 v0, v59
	v_mov_b32_e32 v1, v58
	ds_write_b128 v46, v[0:3]
	ds_write_b128 v46, v[4:7] offset:16
	v_cndmask_b32_e64 v46, 1.0, 0, vcc
	v_cmp_eq_u32_e32 vcc, s11, v78
	s_waitcnt vmcnt(33)
	v_lshlrev_b32_e32 v1, 16, v69
	v_and_b32_e32 v5, s0, v13
	v_cndmask_b32_e64 v47, 1.0, 0, vcc
	v_mul_f32_e32 v55, v47, v1
	s_waitcnt vmcnt(27)
	v_lshlrev_b32_e32 v1, 16, v71
	v_and_b32_e32 v4, 0xffff0000, v12
	v_lshlrev_b32_e32 v53, 16, v13
	v_lshlrev_b32_e32 v0, 16, v68
	v_mul_f32_e32 v56, v46, v1
	v_lshlrev_b32_e32 v1, 16, v70
	v_pk_mov_b32 v[62:63], v[52:53], v[4:5] op_sel:[1,0]
	v_mul_f32_e32 v0, v46, v0
	v_mul_f32_e32 v59, v47, v1
	v_mov_b32_e32 v1, v63
	v_lshlrev_b32_e32 v2, 16, v12
	v_pk_mul_f32 v[0:1], v[30:31], v[0:1]
	v_min_u32_e32 v7, 0x3ff7, v79
	v_pk_fma_f32 v[0:1], v[30:31], v[2:3], v[0:1] op_sel:[0,0,1] op_sel_hi:[1,0,0]
	v_lshlrev_b32_e32 v7, 1, v7
	v_pk_fma_f32 v[4:5], v[28:29], v[62:63], v[0:1] op_sel_hi:[0,1,1]
	v_sub_u32_e64 v0, v79, 1 clamp
	v_lshlrev_b32_e32 v6, 1, v0
	v_lshlrev_b32_e32 v12, 1, v79
	v_lshlrev_b32_e32 v60, 16, v8
	v_and_b32_e32 v67, s0, v9
	v_and_b32_e32 v66, 0xffff0000, v8
	v_lshlrev_b32_e32 v61, 16, v9
	v_pk_mov_b32 v[66:67], v[60:61], v[66:67] op_sel:[1,0]
	v_pk_add_f32 v[64:65], v[32:33], v[4:5] op_sel_hi:[0,1]
	v_mov_b32_e32 v57, v67
	v_pk_mul_f32 v[56:57], v[24:25], v[56:57]
	v_and_b32_e32 v58, 0xffff0000, v11
	v_pk_fma_f32 v[56:57], v[24:25], v[60:61], v[56:57] op_sel:[0,0,1] op_sel_hi:[1,0,0]
	v_and_b32_e32 v73, 16, v10
	v_pk_fma_f32 v[56:57], v[26:27], v[66:67], v[56:57] op_sel_hi:[0,1,1]
	v_pk_add_f32 v[56:57], v[16:17], v[56:57] op_sel_hi:[0,1]
	v_pk_mul_f32 v[64:65], v[64:65], v[56:57]
	v_and_b32_e32 v57, 16, v14
	v_and_b32_e32 v56, 0xffff0000, v13
	v_mov_b32_e32 v68, v56
	v_and_b32_e32 v72, 0xffff0000, v9
	v_lshlrev_b32_e32 v9, 16, v10
	v_and_b32_e32 v75, 16, v11
	v_and_b32_e32 v74, 0xffff0000, v10
	v_lshlrev_b32_e32 v77, 16, v11
	v_pk_mul_f32 v[10:11], v[30:31], v[62:63] op_sel_hi:[0,1]
	v_pk_mul_f32 v[62:63], v[24:25], v[66:67] op_sel_hi:[0,1]
	v_lshlrev_b32_e32 v69, 16, v14
	v_mov_b32_e32 v8, v72
	v_and_b32_e32 v54, 0xffff0000, v15
	v_and_b32_e32 v71, 16, v15
	v_lshlrev_b32_e32 v15, 16, v15
	v_and_b32_e32 v70, 0xffff0000, v14
	v_mov_b32_e32 v14, v70
	v_pk_mov_b32 v[70:71], v[68:69], v[70:71] op_sel:[1,0]
	v_mov_b32_e32 v76, v74
	v_pk_mov_b32 v[74:75], v[8:9], v[74:75] op_sel:[1,0]
	v_cmp_eq_u32_e32 vcc, s87, v29
	v_lshlrev_b32_e32 v79, 2, v79
	v_mul_f32_e32 v21, 0x38000000, v21
	s_waitcnt vmcnt(20)
; #define LAS __attribute__((address_space(3)))
; __device__ __forceinline__ float bflo(unsigned w) { return __uint_as_float(w << 16); }
; __device__ __forceinline__ float bfhi(unsigned w) { return __uint_as_float(w & 0xffff0000u); }
; __device__ __forceinline__ float bf1(bf16 h) { return __uint_as_float((unsigned)h << 16); }
; __device__ __forceinline__ void conv8(const bf16* row, int p0, float c0, float c1, float c2, float cb, float (&o)[8]) {
;     const v4u w = *(const v4u*)(row + p0);
;     float x[10];
;     x[0] = bf1(row[p0 > 0 ? p0 - 1 : 0]) * (p0 > 0 ? 1.f : 0.f); x[9] = bf1(row[p0 + 8 < SEQL ? p0 + 8 : SEQL - 1]) * (p0 + 8 < SEQL ? 1.f : 0.f);
;     x[1] = bflo(w.x); x[2] = bfhi(w.x); x[3] = bflo(w.y); x[4] = bfhi(w.y); x[5] = bflo(w.z); x[6] = bfhi(w.z); x[7] = bflo(w.w); x[8] = bfhi(w.w);
; #pragma unroll
;     for (int e = 0; e < 8; ++e) o[e] = c0 * x[e] + c1 * x[e + 1] + c2 * x[e + 2] + cb;
; }
; template <int VAR> __device__ __forceinline__ void hyena_conv_phase(const Frame& F, const bf16* ZT, const bf16* GT, const float* conv_w, const float* conv_b, const float* skip, float* gscr, float* zscr, bf16* UT) {
;     ...
; #pragma unroll
;         for (int qi = 0; qi < 8; ++qi) { const int q = t + 512 * qi; const int b = qi >> 2, p0 = (q & 2047) * 8; float cv[8], cx[8];
;             conv8(rv + b * SEQL, p0, v0, v1, v2, vb, cv); conv8(rx1 + b * SEQL, p0, b0, b1, b2, bb, cx);
;             f32x4 o0, o1;
; #pragma unroll
;             for (int e = 0; e < 4; ++e) { o0[e] = cv[e] * cx[e]; o1[e] = cv[4 + e] * cx[4 + e]; }
;             *(LAS f32x4*)(X + b * SEQL + p0) = o0; *(LAS f32x4*)(X + b * SEQL + p0 + 4) = o1; }
	v_mov_b32_e32 v80, v86
	v_mov_b32_e32 v0, v134
	v_mov_b32_e32 v1, v135
	v_mov_b32_e32 v2, v136
	v_mov_b32_e32 v3, v137
	v_mov_b32_e32 v81, v88
	v_mov_b32_e32 v49, v90
	v_mov_b32_e32 v50, v92
	v_mov_b32_e32 v82, v94
	v_mov_b32_e32 v52, v96
	v_pk_mov_b32 v[56:57], v[52:53], v[56:57] op_sel:[1,0]
	s_nop 0
	v_pk_fma_f32 v[10:11], v[34:35], v[56:57], v[10:11] op_sel:[0,0,1] op_sel_hi:[0,1,0]
	v_pk_mov_b32 v[56:57], v[60:61], v[72:73] op_sel:[1,0]
	v_pk_fma_f32 v[10:11], v[28:29], v[68:69], v[10:11] op_sel_hi:[0,1,1]
	v_pk_fma_f32 v[56:57], v[36:37], v[56:57], v[62:63] op_sel:[0,0,1] op_sel_hi:[0,1,0]
	v_pk_fma_f32 v[56:57], v[26:27], v[8:9], v[56:57] op_sel_hi:[0,1,1]
	v_pk_add_f32 v[10:11], v[32:33], v[10:11] op_sel_hi:[0,1]
	v_pk_add_f32 v[56:57], v[16:17], v[56:57] op_sel_hi:[0,1]
	v_pk_mul_f32 v[10:11], v[10:11], v[56:57]
	v_mov_b32_e32 v56, v15
	v_mov_b32_e32 v57, v54
	v_pk_mul_f32 v[56:57], v[34:35], v[56:57] op_sel_hi:[0,1]
	v_pk_fma_f32 v[56:57], v[30:31], v[14:15], v[56:57] op_sel_hi:[0,1,1]
	v_pk_fma_f32 v[54:55], v[28:29], v[54:55], v[56:57] op_sel_hi:[0,1,1]
	v_mov_b32_e32 v60, v77
	v_mov_b32_e32 v61, v58
	v_pk_mul_f32 v[62:63], v[34:35], v[70:71] op_sel_hi:[0,1]
	v_pk_add_f32 v[56:57], v[32:33], v[54:55] op_sel_hi:[0,1]
	v_pk_mul_f32 v[54:55], v[36:37], v[74:75] op_sel_hi:[0,1]
	v_pk_fma_f32 v[62:63], v[30:31], v[68:69], v[62:63] op_sel_hi:[0,1,1]
	v_pk_mul_f32 v[60:61], v[36:37], v[60:61] op_sel_hi:[0,1]
	v_pk_fma_f32 v[8:9], v[24:25], v[8:9], v[54:55] op_sel_hi:[0,1,1]
	v_pk_fma_f32 v[14:15], v[28:29], v[14:15], v[62:63] op_sel_hi:[0,1,1]
	v_pk_fma_f32 v[60:61], v[24:25], v[76:77], v[60:61] op_sel_hi:[0,1,1]
	v_pk_fma_f32 v[8:9], v[26:27], v[76:77], v[8:9] op_sel_hi:[0,1,1]
	v_pk_add_f32 v[14:15], v[32:33], v[14:15] op_sel_hi:[0,1]
	v_pk_fma_f32 v[54:55], v[26:27], v[58:59], v[60:61] op_sel_hi:[0,1,1]
	v_pk_add_f32 v[8:9], v[16:17], v[8:9] op_sel_hi:[0,1]
	v_lshlrev_b32_e32 v53, 2, v78
	v_pk_add_f32 v[58:59], v[16:17], v[54:55] op_sel_hi:[0,1]
	v_pk_mul_f32 v[54:55], v[14:15], v[8:9]
	v_add_u32_e32 v13, 0, v53
	v_mov_b32_e32 v8, v65
	v_mov_b32_e32 v9, v64
	v_pk_mul_f32 v[56:57], v[56:57], v[58:59]
	ds_write_b128 v13, v[8:11]
	ds_write_b128 v13, v[54:57] offset:16
	v_lshlrev_b32_e32 v9, 16, v80
	v_cndmask_b32_e64 v8, 1.0, 0, vcc
	v_cmp_eq_u32_e32 vcc, s33, v29
	v_mul_f32_e32 v10, v8, v9
	v_lshlrev_b32_e32 v11, 16, v81
	v_cndmask_b32_e64 v9, 1.0, 0, vcc
	v_mul_f32_e32 v15, v9, v11
	s_waitcnt vmcnt(18)
	v_mov_b32_e32 v51, v98
	v_mov_b32_e32 v83, v100
	v_lshlrev_b32_e32 v11, 16, v83
	v_and_b32_e32 v57, s0, v1
	v_and_b32_e32 v56, 0xffff0000, v0
	v_lshlrev_b32_e32 v13, 16, v1
	v_mul_f32_e32 v62, v8, v11
	v_lshlrev_b32_e32 v11, 16, v82
	v_pk_mov_b32 v[68:69], v[12:13], v[56:57] op_sel:[1,0]
	v_mul_f32_e32 v65, v9, v11
	v_mov_b32_e32 v11, v69
	v_lshlrev_b32_e32 v54, 16, v0
	v_pk_mul_f32 v[10:11], v[30:31], v[10:11]
	v_add_u32_e32 v0, 0x3000, v27
	v_pk_fma_f32 v[10:11], v[30:31], v[54:55], v[10:11] op_sel:[0,0,1] op_sel_hi:[1,0,0]
	s_waitcnt vmcnt(17)
	v_mov_b32_e32 v4, v138
	v_mov_b32_e32 v5, v139
	v_mov_b32_e32 v6, v140
	v_mov_b32_e32 v7, v141
	v_and_b32_e32 v71, s0, v5
	v_pk_fma_f32 v[10:11], v[28:29], v[68:69], v[10:11] op_sel_hi:[0,1,1]
	v_and_b32_e32 v29, 0x3ff8, v0
	v_sub_u32_e64 v0, v29, 1 clamp
	v_lshlrev_b32_e32 v0, 1, v0
	v_min_u32_e32 v27, 0x3ff7, v29
	v_lshlrev_b32_e32 v76, 1, v29
	v_lshlrev_b32_e32 v27, 1, v27
	v_and_b32_e32 v70, 0xffff0000, v4
	v_lshlrev_b32_e32 v27, 16, v5
	v_pk_mov_b32 v[70:71], v[26:27], v[70:71] op_sel:[1,0]
	v_mov_b32_e32 v63, v71
	v_lshlrev_b32_e32 v66, 16, v4
	v_pk_mul_f32 v[62:63], v[24:25], v[62:63]
	v_pk_add_f32 v[10:11], v[32:33], v[10:11] op_sel_hi:[0,1]
	v_pk_fma_f32 v[62:63], v[24:25], v[66:67], v[62:63] op_sel:[0,0,1] op_sel_hi:[1,0,0]
	v_and_b32_e32 v14, 0xffff0000, v3
	v_pk_fma_f32 v[62:63], v[26:27], v[70:71], v[62:63] op_sel_hi:[0,1,1]
	v_pk_add_f32 v[62:63], v[16:17], v[62:63] op_sel_hi:[0,1]
	v_pk_mul_f32 v[10:11], v[10:11], v[62:63]
	v_and_b32_e32 v63, 16, v2
	v_and_b32_e32 v62, 0xffff0000, v1
	v_lshlrev_b32_e32 v1, 16, v2
	v_and_b32_e32 v67, 16, v3
	v_and_b32_e32 v66, 0xffff0000, v2
	v_lshlrev_b32_e32 v73, 16, v3
	v_and_b32_e32 v3, 16, v6
	v_and_b32_e32 v2, 0xffff0000, v5
	v_mov_b32_e32 v0, v62
	v_mov_b32_e32 v4, v2
	v_pk_mul_f32 v[68:69], v[30:31], v[68:69] op_sel_hi:[0,1]
	v_pk_mul_f32 v[70:71], v[24:25], v[70:71] op_sel_hi:[0,1]
	v_pk_mov_b32 v[62:63], v[12:13], v[62:63] op_sel:[1,0]
	v_pk_mov_b32 v[2:3], v[26:27], v[2:3] op_sel:[1,0]
	v_lshlrev_b32_e32 v5, 16, v6
	v_pk_fma_f32 v[62:63], v[34:35], v[62:63], v[68:69] op_sel:[0,0,1] op_sel_hi:[0,1,0]
	v_pk_fma_f32 v[2:3], v[36:37], v[2:3], v[70:71] op_sel:[0,0,1] op_sel_hi:[0,1,0]
	v_pk_fma_f32 v[62:63], v[28:29], v[0:1], v[62:63] op_sel_hi:[0,1,1]
	v_pk_fma_f32 v[2:3], v[26:27], v[4:5], v[2:3] op_sel_hi:[0,1,1]
	v_pk_add_f32 v[62:63], v[32:33], v[62:63] op_sel_hi:[0,1]
	v_pk_add_f32 v[2:3], v[16:17], v[2:3] op_sel_hi:[0,1]
	v_pk_mul_f32 v[2:3], v[62:63], v[2:3]
	v_mov_b32_e32 v62, v73
	v_mov_b32_e32 v63, v14
	v_mov_b32_e32 v72, v66
	v_and_b32_e32 v75, 16, v7
	v_and_b32_e32 v74, 0xffff0000, v6
	v_pk_mul_f32 v[62:63], v[34:35], v[62:63] op_sel_hi:[0,1]
	v_and_b32_e32 v64, 0xffff0000, v7
	v_pk_mov_b32 v[66:67], v[0:1], v[66:67] op_sel:[1,0]
	v_lshlrev_b32_e32 v7, 16, v7
	v_mov_b32_e32 v6, v74
	v_pk_mov_b32 v[74:75], v[4:5], v[74:75] op_sel:[1,0]
	v_pk_fma_f32 v[62:63], v[30:31], v[72:73], v[62:63] op_sel_hi:[0,1,1]
	v_mov_b32_e32 v68, v7
	v_mov_b32_e32 v69, v64
	v_pk_mul_f32 v[66:67], v[34:35], v[66:67] op_sel_hi:[0,1]
	v_pk_fma_f32 v[14:15], v[28:29], v[14:15], v[62:63] op_sel_hi:[0,1,1]
	v_pk_mul_f32 v[62:63], v[36:37], v[74:75] op_sel_hi:[0,1]
	v_pk_fma_f32 v[0:1], v[30:31], v[0:1], v[66:67] op_sel_hi:[0,1,1]
	v_pk_mul_f32 v[66:67], v[36:37], v[68:69] op_sel_hi:[0,1]
	v_pk_fma_f32 v[4:5], v[24:25], v[4:5], v[62:63] op_sel_hi:[0,1,1]
	v_pk_fma_f32 v[0:1], v[28:29], v[72:73], v[0:1] op_sel_hi:[0,1,1]
	v_pk_fma_f32 v[66:67], v[24:25], v[6:7], v[66:67] op_sel_hi:[0,1,1]
	v_pk_fma_f32 v[4:5], v[26:27], v[6:7], v[4:5] op_sel_hi:[0,1,1]
	v_pk_add_f32 v[0:1], v[32:33], v[0:1] op_sel_hi:[0,1]
	v_pk_fma_f32 v[6:7], v[26:27], v[64:65], v[66:67] op_sel_hi:[0,1,1]
	v_pk_add_f32 v[4:5], v[16:17], v[4:5] op_sel_hi:[0,1]
	v_pk_add_f32 v[14:15], v[32:33], v[14:15] op_sel_hi:[0,1]
	v_pk_add_f32 v[6:7], v[16:17], v[6:7] op_sel_hi:[0,1]
	v_pk_mul_f32 v[4:5], v[0:1], v[4:5]
	v_add_u32_e32 v13, 0, v79
	v_mov_b32_e32 v0, v11
	v_mov_b32_e32 v1, v10
	v_cmp_eq_u32_e32 vcc, 0, v29
	v_pk_mul_f32 v[6:7], v[14:15], v[6:7]
	ds_write_b128 v13, v[0:3]
	ds_write_b128 v13, v[4:7] offset:16
	s_add_u32 s90, s16, s82
	s_addc_u32 s91, s17, s83
	s_waitcnt vmcnt(16)
; #define LAS __attribute__((address_space(3)))
; __device__ __forceinline__ float bflo(unsigned w) { return __uint_as_float(w << 16); }
; __device__ __forceinline__ float bfhi(unsigned w) { return __uint_as_float(w & 0xffff0000u); }
; __device__ __forceinline__ float bf1(bf16 h) { return __uint_as_float((unsigned)h << 16); }
; __device__ __forceinline__ void conv8(const bf16* row, int p0, float c0, float c1, float c2, float cb, float (&o)[8]) {
;     const v4u w = *(const v4u*)(row + p0);
;     float x[10];
;     x[0] = bf1(row[p0 > 0 ? p0 - 1 : 0]) * (p0 > 0 ? 1.f : 0.f); x[9] = bf1(row[p0 + 8 < SEQL ? p0 + 8 : SEQL - 1]) * (p0 + 8 < SEQL ? 1.f : 0.f);
;     x[1] = bflo(w.x); x[2] = bfhi(w.x); x[3] = bflo(w.y); x[4] = bfhi(w.y); x[5] = bflo(w.z); x[6] = bfhi(w.z); x[7] = bflo(w.w); x[8] = bfhi(w.w);
; #pragma unroll
;     for (int e = 0; e < 8; ++e) o[e] = c0 * x[e] + c1 * x[e + 1] + c2 * x[e + 2] + cb;
; }
; template <int VAR> __device__ __forceinline__ void hyena_conv_phase(const Frame& F, const bf16* ZT, const bf16* GT, const float* conv_w, const float* conv_b, const float* skip, float* gscr, float* zscr, bf16* UT) {
;     ...
; #pragma unroll
;         for (int qi = 0; qi < 8; ++qi) { const int q = t + 512 * qi; const int b = qi >> 2, p0 = (q & 2047) * 8; float cv[8], cx[8];
;             conv8(rv + b * SEQL, p0, v0, v1, v2, vb, cv); conv8(rx1 + b * SEQL, p0, b0, b1, b2, bb, cx);
;             f32x4 o0, o1;
; #pragma unroll
;             for (int e = 0; e < 4; ++e) { o0[e] = cv[e] * cx[e]; o1[e] = cv[4 + e] * cx[4 + e]; }
;             *(LAS f32x4*)(X + b * SEQL + p0) = o0; *(LAS f32x4*)(X + b * SEQL + p0 + 4) = o1; }
	v_mov_b32_e32 v77, v102
	v_lshlrev_b32_e32 v0, 16, v77
	v_cndmask_b32_e64 v77, 1.0, 0, vcc
	v_cmp_eq_u32_e32 vcc, s11, v29
	v_mul_f32_e32 v4, v77, v0
	s_waitcnt vmcnt(14)
	v_mov_b32_e32 v54, v142
	v_mov_b32_e32 v55, v143
	v_mov_b32_e32 v56, v144
	v_mov_b32_e32 v57, v145
	v_mov_b32_e32 v78, v104
	v_lshlrev_b32_e32 v0, 16, v78
	v_cndmask_b32_e64 v78, 1.0, 0, vcc
	v_mul_f32_e32 v11, v78, v0
	s_waitcnt vmcnt(8)
	v_mov_b32_e32 v80, v106
	v_mov_b32_e32 v81, v108
	v_mov_b32_e32 v82, v110
	v_mov_b32_e32 v83, v112
	v_mov_b32_e32 v84, v114
	v_mov_b32_e32 v85, v116
	v_lshlrev_b32_e32 v0, 16, v85
	v_mul_f32_e32 v14, v77, v0
	v_lshlrev_b32_e32 v0, 16, v82
	v_mul_f32_e32 v63, v78, v0
	v_and_b32_e32 v67, s0, v55
	v_and_b32_e32 v66, 0xffff0000, v54
	v_lshlrev_b32_e32 v13, 16, v55
	v_pk_mov_b32 v[66:67], v[12:13], v[66:67] op_sel:[1,0]
	v_lshlrev_b32_e32 v6, 16, v54
	v_mov_b32_e32 v5, v67
	v_pk_mul_f32 v[4:5], v[30:31], v[4:5]
	s_waitcnt vmcnt(7)
	v_mov_b32_e32 v58, v146
	v_mov_b32_e32 v59, v147
	v_mov_b32_e32 v60, v148
	v_mov_b32_e32 v61, v149
	v_and_b32_e32 v71, s0, v59
	v_pk_fma_f32 v[68:69], v[30:31], v[6:7], v[4:5] op_sel:[0,0,1] op_sel_hi:[1,0,0]
	v_and_b32_e32 v70, 0xffff0000, v58
	v_lshlrev_b32_e32 v23, 16, v59
	v_pk_mov_b32 v[70:71], v[22:23], v[70:71] op_sel:[1,0]
	v_lshlrev_b32_e32 v64, 16, v58
	v_mov_b32_e32 v15, v71
	v_pk_mul_f32 v[14:15], v[24:25], v[14:15]
	v_pk_fma_f32 v[68:69], v[28:29], v[66:67], v[68:69] op_sel_hi:[0,1,1]
	v_pk_fma_f32 v[14:15], v[24:25], v[64:65], v[14:15] op_sel:[0,0,1] op_sel_hi:[1,0,0]
	v_pk_add_f32 v[68:69], v[32:33], v[68:69] op_sel_hi:[0,1]
	v_pk_fma_f32 v[14:15], v[26:27], v[70:71], v[14:15] op_sel_hi:[0,1,1]
	v_pk_add_f32 v[14:15], v[16:17], v[14:15] op_sel_hi:[0,1]
	v_and_b32_e32 v10, 0xffff0000, v57
	v_pk_mul_f32 v[14:15], v[68:69], v[14:15]
	v_and_b32_e32 v65, 16, v56
	v_and_b32_e32 v64, 0xffff0000, v55
	v_lshlrev_b32_e32 v55, 16, v56
	v_and_b32_e32 v69, 16, v57
	v_and_b32_e32 v68, 0xffff0000, v56
	v_lshlrev_b32_e32 v73, 16, v57
	v_and_b32_e32 v57, 16, v60
	v_and_b32_e32 v56, 0xffff0000, v59
	v_mov_b32_e32 v54, v64
	v_mov_b32_e32 v58, v56
	v_pk_mul_f32 v[66:67], v[30:31], v[66:67] op_sel_hi:[0,1]
	v_pk_mul_f32 v[70:71], v[24:25], v[70:71] op_sel_hi:[0,1]
	v_pk_mov_b32 v[64:65], v[12:13], v[64:65] op_sel:[1,0]
	v_pk_mov_b32 v[56:57], v[22:23], v[56:57] op_sel:[1,0]
	v_lshlrev_b32_e32 v59, 16, v60
	v_pk_fma_f32 v[64:65], v[34:35], v[64:65], v[66:67] op_sel:[0,0,1] op_sel_hi:[0,1,0]
	v_pk_fma_f32 v[56:57], v[36:37], v[56:57], v[70:71] op_sel:[0,0,1] op_sel_hi:[0,1,0]
	v_pk_fma_f32 v[64:65], v[28:29], v[54:55], v[64:65] op_sel_hi:[0,1,1]
	v_pk_fma_f32 v[56:57], v[26:27], v[58:59], v[56:57] op_sel_hi:[0,1,1]
	v_pk_add_f32 v[64:65], v[32:33], v[64:65] op_sel_hi:[0,1]
	v_pk_add_f32 v[56:57], v[16:17], v[56:57] op_sel_hi:[0,1]
	v_pk_mul_f32 v[56:57], v[64:65], v[56:57]
	v_mov_b32_e32 v64, v73
	v_mov_b32_e32 v65, v10
	v_and_b32_e32 v62, 0xffff0000, v61
	v_mov_b32_e32 v72, v68
	v_and_b32_e32 v75, 16, v61
	v_and_b32_e32 v74, 0xffff0000, v60
	v_lshlrev_b32_e32 v61, 16, v61
	v_pk_mul_f32 v[64:65], v[34:35], v[64:65] op_sel_hi:[0,1]
	v_mov_b32_e32 v60, v74
	v_pk_mov_b32 v[74:75], v[58:59], v[74:75] op_sel:[1,0]
	v_mov_b32_e32 v66, v61
	v_mov_b32_e32 v67, v62
	v_pk_fma_f32 v[64:65], v[30:31], v[72:73], v[64:65] op_sel_hi:[0,1,1]
	v_pk_mov_b32 v[68:69], v[54:55], v[68:69] op_sel:[1,0]
	v_pk_fma_f32 v[10:11], v[28:29], v[10:11], v[64:65] op_sel_hi:[0,1,1]
	v_pk_mul_f32 v[64:65], v[36:37], v[74:75] op_sel_hi:[0,1]
	v_pk_mul_f32 v[66:67], v[36:37], v[66:67] op_sel_hi:[0,1]
	v_pk_mul_f32 v[68:69], v[34:35], v[68:69] op_sel_hi:[0,1]
	v_pk_fma_f32 v[66:67], v[24:25], v[60:61], v[66:67] op_sel_hi:[0,1,1]
	v_pk_fma_f32 v[58:59], v[24:25], v[58:59], v[64:65] op_sel_hi:[0,1,1]
	v_pk_fma_f32 v[54:55], v[30:31], v[54:55], v[68:69] op_sel_hi:[0,1,1]
	v_pk_fma_f32 v[58:59], v[26:27], v[60:61], v[58:59] op_sel_hi:[0,1,1]
	v_pk_fma_f32 v[60:61], v[26:27], v[62:63], v[66:67] op_sel_hi:[0,1,1]
	v_pk_fma_f32 v[54:55], v[28:29], v[72:73], v[54:55] op_sel_hi:[0,1,1]
	v_pk_add_f32 v[10:11], v[32:33], v[10:11] op_sel_hi:[0,1]
	v_pk_add_f32 v[60:61], v[16:17], v[60:61] op_sel_hi:[0,1]
	v_pk_add_f32 v[54:55], v[32:33], v[54:55] op_sel_hi:[0,1]
	v_pk_add_f32 v[58:59], v[16:17], v[58:59] op_sel_hi:[0,1]
	v_pk_mul_f32 v[60:61], v[10:11], v[60:61]
	v_lshlrev_b32_e32 v29, 2, v29
	v_lshlrev_b32_e32 v11, 16, v39
	v_pk_mul_f32 v[58:59], v[54:55], v[58:59]
	v_add_u32_e32 v10, 0, v29
	v_mov_b32_e32 v54, v15
	v_mov_b32_e32 v55, v14
	v_mul_f32_e32 v15, v41, v11
	v_lshlrev_b32_e32 v11, 16, v33
	ds_write_b128 v10, v[54:57]
	ds_write_b128 v10, v[58:61] offset:16
	v_lshlrev_b32_e32 v10, 16, v37
	v_mul_f32_e32 v60, v40, v11
	v_lshlrev_b32_e32 v11, 16, v38
	v_mul_f32_e32 v10, v40, v10
	v_mul_f32_e32 v63, v41, v11
	s_waitcnt vmcnt(6)
	v_mov_b32_e32 v0, v212
	v_mov_b32_e32 v1, v213
	v_mov_b32_e32 v2, v214
	v_mov_b32_e32 v3, v215
	v_and_b32_e32 v55, s0, v1
	v_and_b32_e32 v54, 0xffff0000, v0
	v_lshlrev_b32_e32 v13, 16, v1
	v_pk_mov_b32 v[66:67], v[12:13], v[54:55] op_sel:[1,0]
	v_lshlrev_b32_e32 v58, 16, v0
	v_mov_b32_e32 v11, v67
	v_pk_mul_f32 v[10:11], v[30:31], v[10:11]
	v_pk_fma_f32 v[10:11], v[30:31], v[58:59], v[10:11] op_sel:[0,0,1] op_sel_hi:[1,0,0]
	s_waitcnt vmcnt(5)
; #define LAS __attribute__((address_space(3)))
; __device__ __forceinline__ float bflo(unsigned w) { return __uint_as_float(w << 16); }
; __device__ __forceinline__ float bfhi(unsigned w) { return __uint_as_float(w & 0xffff0000u); }
; __device__ __forceinline__ float bf1(bf16 h) { return __uint_as_float((unsigned)h << 16); }
; __device__ __forceinline__ void conv8(const bf16* row, int p0, float c0, float c1, float c2, float cb, float (&o)[8]) {
;     const v4u w = *(const v4u*)(row + p0);
;     float x[10];
;     x[0] = bf1(row[p0 > 0 ? p0 - 1 : 0]) * (p0 > 0 ? 1.f : 0.f); x[9] = bf1(row[p0 + 8 < SEQL ? p0 + 8 : SEQL - 1]) * (p0 + 8 < SEQL ? 1.f : 0.f);
;     x[1] = bflo(w.x); x[2] = bfhi(w.x); x[3] = bflo(w.y); x[4] = bfhi(w.y); x[5] = bflo(w.z); x[6] = bfhi(w.z); x[7] = bflo(w.w); x[8] = bfhi(w.w);
; #pragma unroll
;     for (int e = 0; e < 8; ++e) o[e] = c0 * x[e] + c1 * x[e + 1] + c2 * x[e + 2] + cb;
; }
; template <int VAR> __device__ __forceinline__ void hyena_conv_phase(const Frame& F, const bf16* ZT, const bf16* GT, const float* conv_w, const float* conv_b, const float* skip, float* gscr, float* zscr, bf16* UT) {
;     ...
; #pragma unroll
;         for (int qi = 0; qi < 8; ++qi) { const int q = t + 512 * qi; const int b = qi >> 2, p0 = (q & 2047) * 8; float cv[8], cx[8];
;             conv8(rv + b * SEQL, p0, v0, v1, v2, vb, cv); conv8(rx1 + b * SEQL, p0, b0, b1, b2, bb, cx);
;             f32x4 o0, o1;
; #pragma unroll
;             for (int e = 0; e < 4; ++e) { o0[e] = cv[e] * cx[e]; o1[e] = cv[4 + e] * cx[4 + e]; }
;             *(LAS f32x4*)(X + b * SEQL + p0) = o0; *(LAS f32x4*)(X + b * SEQL + p0 + 4) = o1; }
	v_mov_b32_e32 v4, v222
	v_mov_b32_e32 v5, v223
	v_mov_b32_e32 v6, v224
	v_mov_b32_e32 v7, v225
	v_and_b32_e32 v59, s0, v5
	v_and_b32_e32 v58, 0xffff0000, v4
	v_lshlrev_b32_e32 v23, 16, v5
	v_pk_mov_b32 v[58:59], v[22:23], v[58:59] op_sel:[1,0]
	v_lshlrev_b32_e32 v64, 16, v4
	v_mov_b32_e32 v61, v59
	v_pk_mul_f32 v[60:61], v[24:25], v[60:61]
	v_pk_fma_f32 v[10:11], v[28:29], v[66:67], v[10:11] op_sel_hi:[0,1,1]
	v_pk_fma_f32 v[60:61], v[24:25], v[64:65], v[60:61] op_sel:[0,0,1] op_sel_hi:[1,0,0]
	v_pk_add_f32 v[10:11], v[32:33], v[10:11] op_sel_hi:[0,1]
	v_pk_fma_f32 v[60:61], v[26:27], v[58:59], v[60:61] op_sel_hi:[0,1,1]
	v_pk_add_f32 v[60:61], v[16:17], v[60:61] op_sel_hi:[0,1]
	v_and_b32_e32 v14, 0xffff0000, v3
	v_pk_mul_f32 v[10:11], v[10:11], v[60:61]
	v_and_b32_e32 v61, 16, v2
	v_and_b32_e32 v60, 0xffff0000, v1
	v_lshlrev_b32_e32 v1, 16, v2
	v_and_b32_e32 v65, 16, v3
	v_and_b32_e32 v64, 0xffff0000, v2
	v_lshlrev_b32_e32 v69, 16, v3
	v_and_b32_e32 v3, 16, v6
	v_and_b32_e32 v2, 0xffff0000, v5
	v_mov_b32_e32 v0, v60
	v_mov_b32_e32 v4, v2
	v_pk_mul_f32 v[66:67], v[30:31], v[66:67] op_sel_hi:[0,1]
	v_pk_mul_f32 v[58:59], v[24:25], v[58:59] op_sel_hi:[0,1]
	v_pk_mov_b32 v[60:61], v[12:13], v[60:61] op_sel:[1,0]
	v_pk_mov_b32 v[2:3], v[22:23], v[2:3] op_sel:[1,0]
	v_lshlrev_b32_e32 v5, 16, v6
	v_pk_fma_f32 v[60:61], v[34:35], v[60:61], v[66:67] op_sel:[0,0,1] op_sel_hi:[0,1,0]
	v_pk_fma_f32 v[2:3], v[36:37], v[2:3], v[58:59] op_sel:[0,0,1] op_sel_hi:[0,1,0]
	v_mov_b32_e32 v58, v69
	v_mov_b32_e32 v59, v14
	v_mov_b32_e32 v68, v64
	v_and_b32_e32 v71, 16, v7
	v_and_b32_e32 v70, 0xffff0000, v6
	v_pk_fma_f32 v[60:61], v[28:29], v[0:1], v[60:61] op_sel_hi:[0,1,1]
	v_pk_fma_f32 v[2:3], v[26:27], v[4:5], v[2:3] op_sel_hi:[0,1,1]
	v_pk_mul_f32 v[58:59], v[34:35], v[58:59] op_sel_hi:[0,1]
	v_and_b32_e32 v62, 0xffff0000, v7
	v_pk_mov_b32 v[64:65], v[0:1], v[64:65] op_sel:[1,0]
	v_lshlrev_b32_e32 v7, 16, v7
	v_mov_b32_e32 v6, v70
	v_pk_mov_b32 v[70:71], v[4:5], v[70:71] op_sel:[1,0]
	v_pk_add_f32 v[60:61], v[32:33], v[60:61] op_sel_hi:[0,1]
	v_pk_add_f32 v[2:3], v[16:17], v[2:3] op_sel_hi:[0,1]
	v_pk_fma_f32 v[58:59], v[30:31], v[68:69], v[58:59] op_sel_hi:[0,1,1]
	v_pk_mul_f32 v[2:3], v[60:61], v[2:3]
	v_mov_b32_e32 v60, v7
	v_mov_b32_e32 v61, v62
	v_pk_mul_f32 v[64:65], v[34:35], v[64:65] op_sel_hi:[0,1]
	v_pk_fma_f32 v[14:15], v[28:29], v[14:15], v[58:59] op_sel_hi:[0,1,1]
	v_pk_mul_f32 v[58:59], v[36:37], v[70:71] op_sel_hi:[0,1]
	v_pk_fma_f32 v[0:1], v[30:31], v[0:1], v[64:65] op_sel_hi:[0,1,1]
	v_pk_mul_f32 v[60:61], v[36:37], v[60:61] op_sel_hi:[0,1]
	v_pk_fma_f32 v[4:5], v[24:25], v[4:5], v[58:59] op_sel_hi:[0,1,1]
	v_pk_fma_f32 v[0:1], v[28:29], v[68:69], v[0:1] op_sel_hi:[0,1,1]
	v_pk_fma_f32 v[60:61], v[24:25], v[6:7], v[60:61] op_sel_hi:[0,1,1]
	v_pk_fma_f32 v[4:5], v[26:27], v[6:7], v[4:5] op_sel_hi:[0,1,1]
	v_pk_add_f32 v[0:1], v[32:33], v[0:1] op_sel_hi:[0,1]
	v_pk_fma_f32 v[6:7], v[26:27], v[62:63], v[60:61] op_sel_hi:[0,1,1]
	v_pk_add_f32 v[4:5], v[16:17], v[4:5] op_sel_hi:[0,1]
	v_pk_add_f32 v[14:15], v[32:33], v[14:15] op_sel_hi:[0,1]
	v_pk_add_f32 v[6:7], v[16:17], v[6:7] op_sel_hi:[0,1]
	v_pk_mul_f32 v[4:5], v[0:1], v[4:5]
	v_add_u32_e32 v13, s85, v48
	v_mov_b32_e32 v0, v11
	v_mov_b32_e32 v1, v10
	v_pk_mul_f32 v[6:7], v[14:15], v[6:7]
	ds_write_b128 v13, v[0:3]
	ds_write_b128 v13, v[4:7] offset:16
	v_lshlrev_b32_e32 v0, 16, v45
	v_mul_f32_e32 v4, v46, v0
	v_lshlrev_b32_e32 v0, 16, v42
	v_mul_f32_e32 v11, v47, v0
	v_lshlrev_b32_e32 v0, 16, v44
	v_mul_f32_e32 v42, v46, v0
	v_lshlrev_b32_e32 v0, 16, v43
	v_mul_f32_e32 v45, v47, v0
	s_waitcnt vmcnt(4)
	v_mov_b32_e32 v38, v226
	v_mov_b32_e32 v39, v227
	v_mov_b32_e32 v40, v228
	v_mov_b32_e32 v41, v229
	v_and_b32_e32 v7, s0, v39
	v_and_b32_e32 v6, 0xffff0000, v38
	v_lshlrev_b32_e32 v13, 16, v39
	v_pk_mov_b32 v[58:59], v[12:13], v[6:7] op_sel:[1,0]
	v_lshlrev_b32_e32 v14, 16, v38
	v_mov_b32_e32 v5, v59
	v_pk_mul_f32 v[60:61], v[30:31], v[4:5]
	s_waitcnt vmcnt(3)
	v_mov_b32_e32 v54, v236
	v_mov_b32_e32 v55, v237
	v_mov_b32_e32 v56, v238
	v_mov_b32_e32 v57, v239
	v_lshlrev_b32_e32 v23, 16, v55
	v_pk_fma_f32 v[14:15], v[30:31], v[14:15], v[60:61] op_sel:[0,0,1] op_sel_hi:[1,0,0]
	v_and_b32_e32 v61, s0, v55
	v_and_b32_e32 v60, 0xffff0000, v54
	v_pk_mov_b32 v[60:61], v[22:23], v[60:61] op_sel:[1,0]
	v_lshlrev_b32_e32 v46, 16, v54
	v_mov_b32_e32 v43, v61
	v_pk_mul_f32 v[42:43], v[24:25], v[42:43]
	v_pk_fma_f32 v[14:15], v[28:29], v[58:59], v[14:15] op_sel_hi:[0,1,1]
	v_pk_fma_f32 v[42:43], v[24:25], v[46:47], v[42:43] op_sel:[0,0,1] op_sel_hi:[1,0,0]
	v_pk_add_f32 v[14:15], v[32:33], v[14:15] op_sel_hi:[0,1]
	v_pk_fma_f32 v[42:43], v[26:27], v[60:61], v[42:43] op_sel_hi:[0,1,1]
	v_pk_add_f32 v[42:43], v[16:17], v[42:43] op_sel_hi:[0,1]
	v_pk_mul_f32 v[14:15], v[14:15], v[42:43]
	v_and_b32_e32 v43, 16, v40
	v_and_b32_e32 v42, 0xffff0000, v39
	v_and_b32_e32 v63, 16, v56
	v_and_b32_e32 v62, 0xffff0000, v55
	v_mov_b32_e32 v38, v42
	v_pk_mul_f32 v[58:59], v[30:31], v[58:59] op_sel_hi:[0,1]
	v_pk_mul_f32 v[60:61], v[24:25], v[60:61] op_sel_hi:[0,1]
	v_pk_mov_b32 v[12:13], v[12:13], v[42:43] op_sel:[1,0]
	v_pk_mov_b32 v[42:43], v[22:23], v[62:63] op_sel:[1,0]
	v_lshlrev_b32_e32 v39, 16, v40
	v_lshlrev_b32_e32 v55, 16, v56
	v_mov_b32_e32 v54, v62
	v_pk_fma_f32 v[12:13], v[34:35], v[12:13], v[58:59] op_sel:[0,0,1] op_sel_hi:[0,1,0]
	v_pk_fma_f32 v[42:43], v[36:37], v[42:43], v[60:61] op_sel:[0,0,1] op_sel_hi:[0,1,0]
	v_pk_fma_f32 v[12:13], v[28:29], v[38:39], v[12:13] op_sel_hi:[0,1,1]
	v_pk_fma_f32 v[42:43], v[26:27], v[54:55], v[42:43] op_sel_hi:[0,1,1]
	v_and_b32_e32 v10, 0xffff0000, v41
; #define LAS __attribute__((address_space(3)))
; __device__ __forceinline__ float bflo(unsigned w) { return __uint_as_float(w << 16); }
; __device__ __forceinline__ float bfhi(unsigned w) { return __uint_as_float(w & 0xffff0000u); }
; __device__ __forceinline__ float bf1(bf16 h) { return __uint_as_float((unsigned)h << 16); }
; __device__ __forceinline__ void conv8(const bf16* row, int p0, float c0, float c1, float c2, float cb, float (&o)[8]) {
;     const v4u w = *(const v4u*)(row + p0);
;     float x[10];
;     x[0] = bf1(row[p0 > 0 ? p0 - 1 : 0]) * (p0 > 0 ? 1.f : 0.f); x[9] = bf1(row[p0 + 8 < SEQL ? p0 + 8 : SEQL - 1]) * (p0 + 8 < SEQL ? 1.f : 0.f);
;     x[1] = bflo(w.x); x[2] = bfhi(w.x); x[3] = bflo(w.y); x[4] = bfhi(w.y); x[5] = bflo(w.z); x[6] = bfhi(w.z); x[7] = bflo(w.w); x[8] = bfhi(w.w);
; #pragma unroll
;     for (int e = 0; e < 8; ++e) o[e] = c0 * x[e] + c1 * x[e + 1] + c2 * x[e + 2] + cb;
; }
; template <int VAR> __device__ __forceinline__ void hyena_conv_phase(const Frame& F, const bf16* ZT, const bf16* GT, const float* conv_w, const float* conv_b, const float* skip, float* gscr, float* zscr, bf16* UT) {
;     ...
; #pragma unroll
;         for (int qi = 0; qi < 8; ++qi) { const int q = t + 512 * qi; const int b = qi >> 2, p0 = (q & 2047) * 8; float cv[8], cx[8];
;             conv8(rv + b * SEQL, p0, v0, v1, v2, vb, cv); conv8(rx1 + b * SEQL, p0, b0, b1, b2, bb, cx);
;             f32x4 o0, o1;
; #pragma unroll
;             for (int e = 0; e < 4; ++e) { o0[e] = cv[e] * cx[e]; o1[e] = cv[4 + e] * cx[4 + e]; }
;             *(LAS f32x4*)(X + b * SEQL + p0) = o0; *(LAS f32x4*)(X + b * SEQL + p0 + 4) = o1; }
	v_and_b32_e32 v47, 16, v41
	v_and_b32_e32 v46, 0xffff0000, v40
	v_lshlrev_b32_e32 v41, 16, v41
	v_pk_add_f32 v[12:13], v[32:33], v[12:13] op_sel_hi:[0,1]
	v_pk_add_f32 v[42:43], v[16:17], v[42:43] op_sel_hi:[0,1]
	v_mov_b32_e32 v40, v46
	v_pk_mov_b32 v[46:47], v[38:39], v[46:47] op_sel:[1,0]
	v_pk_mul_f32 v[12:13], v[12:13], v[42:43]
	v_mov_b32_e32 v42, v41
	v_mov_b32_e32 v43, v10
	v_and_b32_e32 v44, 0xffff0000, v57
	v_and_b32_e32 v65, 16, v57
	v_and_b32_e32 v64, 0xffff0000, v56
	v_lshlrev_b32_e32 v57, 16, v57
	v_pk_mul_f32 v[46:47], v[34:35], v[46:47] op_sel_hi:[0,1]
	v_pk_mul_f32 v[42:43], v[34:35], v[42:43] op_sel_hi:[0,1]
	v_mov_b32_e32 v56, v64
	v_pk_mov_b32 v[64:65], v[54:55], v[64:65] op_sel:[1,0]
	v_mov_b32_e32 v58, v57
	v_mov_b32_e32 v59, v44
	v_pk_fma_f32 v[42:43], v[30:31], v[40:41], v[42:43] op_sel_hi:[0,1,1]
	v_pk_fma_f32 v[38:39], v[30:31], v[38:39], v[46:47] op_sel_hi:[0,1,1]
	v_pk_fma_f32 v[38:39], v[28:29], v[40:41], v[38:39] op_sel_hi:[0,1,1]
	v_pk_fma_f32 v[10:11], v[28:29], v[10:11], v[42:43] op_sel_hi:[0,1,1]
	v_pk_mul_f32 v[40:41], v[36:37], v[64:65] op_sel_hi:[0,1]
	v_pk_mul_f32 v[42:43], v[36:37], v[58:59] op_sel_hi:[0,1]
	v_pk_fma_f32 v[42:43], v[24:25], v[56:57], v[42:43] op_sel_hi:[0,1,1]
	v_pk_fma_f32 v[40:41], v[24:25], v[54:55], v[40:41] op_sel_hi:[0,1,1]
	v_pk_fma_f32 v[40:41], v[26:27], v[56:57], v[40:41] op_sel_hi:[0,1,1]
	v_pk_fma_f32 v[42:43], v[26:27], v[44:45], v[42:43] op_sel_hi:[0,1,1]
	v_pk_add_f32 v[10:11], v[32:33], v[10:11] op_sel_hi:[0,1]
	v_pk_add_f32 v[38:39], v[32:33], v[38:39] op_sel_hi:[0,1]
	v_pk_add_f32 v[42:43], v[16:17], v[42:43] op_sel_hi:[0,1]
	v_pk_add_f32 v[40:41], v[16:17], v[40:41] op_sel_hi:[0,1]
	v_pk_mul_f32 v[38:39], v[38:39], v[40:41]
	v_pk_mul_f32 v[40:41], v[10:11], v[42:43]
	v_add_u32_e32 v23, s85, v53
	v_mov_b32_e32 v10, v15
	v_mov_b32_e32 v11, v14
	ds_write_b128 v23, v[10:13]
	ds_write_b128 v23, v[38:41] offset:16
	v_lshlrev_b32_e32 v10, 16, v52
	v_mul_f32_e32 v12, v8, v10
	v_lshlrev_b32_e32 v10, 16, v49
	s_waitcnt vmcnt(2)
	v_mov_b32_e32 v0, v240
	v_mov_b32_e32 v1, v241
	v_mov_b32_e32 v2, v242
	v_mov_b32_e32 v3, v243
	v_and_b32_e32 v15, s0, v1
	v_and_b32_e32 v14, 0xffff0000, v0
	v_lshlrev_b32_e32 v23, 16, v1
	v_mul_f32_e32 v39, v9, v10
	v_lshlrev_b32_e32 v10, 16, v51
	v_pk_mov_b32 v[48:49], v[22:23], v[14:15] op_sel:[1,0]
	v_mul_f32_e32 v42, v8, v10
	v_lshlrev_b32_e32 v8, 16, v50
	v_mov_b32_e32 v13, v49
	v_mul_f32_e32 v45, v9, v8
	v_pk_mul_f32 v[50:51], v[30:31], v[12:13]
	global_load_dwordx4 v[12:15], v76, s[96:97]
	v_lshlrev_b32_e32 v40, 16, v0
	v_pk_fma_f32 v[40:41], v[30:31], v[40:41], v[50:51] op_sel:[0,0,1] op_sel_hi:[1,0,0]
	s_waitcnt vmcnt(2)
	v_mov_b32_e32 v4, v244
	v_mov_b32_e32 v5, v245
	v_mov_b32_e32 v6, v246
	v_mov_b32_e32 v7, v247
	v_and_b32_e32 v51, s0, v5
	v_and_b32_e32 v50, 0xffff0000, v4
	v_lshlrev_b32_e32 v27, 16, v5
	v_pk_mov_b32 v[50:51], v[26:27], v[50:51] op_sel:[1,0]
	v_lshlrev_b32_e32 v46, 16, v4
	v_mov_b32_e32 v43, v51
	v_pk_mul_f32 v[42:43], v[24:25], v[42:43]
	v_pk_fma_f32 v[40:41], v[28:29], v[48:49], v[40:41] op_sel_hi:[0,1,1]
	v_pk_fma_f32 v[42:43], v[24:25], v[46:47], v[42:43] op_sel:[0,0,1] op_sel_hi:[1,0,0]
	v_pk_add_f32 v[40:41], v[32:33], v[40:41] op_sel_hi:[0,1]
	v_pk_fma_f32 v[42:43], v[26:27], v[50:51], v[42:43] op_sel_hi:[0,1,1]
	v_pk_add_f32 v[42:43], v[16:17], v[42:43] op_sel_hi:[0,1]
	v_and_b32_e32 v38, 0xffff0000, v3
	v_pk_mul_f32 v[40:41], v[40:41], v[42:43]
	v_and_b32_e32 v43, 16, v2
	v_and_b32_e32 v42, 0xffff0000, v1
	v_lshlrev_b32_e32 v1, 16, v2
	v_and_b32_e32 v47, 16, v3
	v_and_b32_e32 v46, 0xffff0000, v2
	v_lshlrev_b32_e32 v53, 16, v3
	v_and_b32_e32 v3, 16, v6
	v_and_b32_e32 v2, 0xffff0000, v5
	v_mov_b32_e32 v0, v42
	v_mov_b32_e32 v4, v2
	v_pk_mul_f32 v[48:49], v[30:31], v[48:49] op_sel_hi:[0,1]
	v_pk_mul_f32 v[50:51], v[24:25], v[50:51] op_sel_hi:[0,1]
	v_pk_mov_b32 v[42:43], v[22:23], v[42:43] op_sel:[1,0]
	v_pk_mov_b32 v[2:3], v[26:27], v[2:3] op_sel:[1,0]
	v_lshlrev_b32_e32 v5, 16, v6
	v_pk_fma_f32 v[42:43], v[34:35], v[42:43], v[48:49] op_sel:[0,0,1] op_sel_hi:[0,1,0]
	v_pk_fma_f32 v[2:3], v[36:37], v[2:3], v[50:51] op_sel:[0,0,1] op_sel_hi:[0,1,0]
	v_pk_fma_f32 v[42:43], v[28:29], v[0:1], v[42:43] op_sel_hi:[0,1,1]
	v_pk_fma_f32 v[2:3], v[26:27], v[4:5], v[2:3] op_sel_hi:[0,1,1]
	v_pk_add_f32 v[42:43], v[32:33], v[42:43] op_sel_hi:[0,1]
	v_pk_add_f32 v[2:3], v[16:17], v[2:3] op_sel_hi:[0,1]
	v_pk_mul_f32 v[2:3], v[42:43], v[2:3]
	v_mov_b32_e32 v42, v53
	v_mov_b32_e32 v43, v38
	v_mov_b32_e32 v52, v46
	v_and_b32_e32 v55, 16, v7
	v_and_b32_e32 v54, 0xffff0000, v6
	v_pk_mul_f32 v[42:43], v[34:35], v[42:43] op_sel_hi:[0,1]
	v_and_b32_e32 v44, 0xffff0000, v7
	v_pk_mov_b32 v[46:47], v[0:1], v[46:47] op_sel:[1,0]
	v_lshlrev_b32_e32 v7, 16, v7
	v_mov_b32_e32 v6, v54
	v_pk_mov_b32 v[54:55], v[4:5], v[54:55] op_sel:[1,0]
	v_pk_fma_f32 v[42:43], v[30:31], v[52:53], v[42:43] op_sel_hi:[0,1,1]
	v_mov_b32_e32 v48, v7
	v_mov_b32_e32 v49, v44
	v_pk_mul_f32 v[46:47], v[34:35], v[46:47] op_sel_hi:[0,1]
	v_pk_fma_f32 v[38:39], v[28:29], v[38:39], v[42:43] op_sel_hi:[0,1,1]
	v_pk_mul_f32 v[42:43], v[36:37], v[54:55] op_sel_hi:[0,1]
	v_pk_fma_f32 v[0:1], v[30:31], v[0:1], v[46:47] op_sel_hi:[0,1,1]
	v_pk_mul_f32 v[46:47], v[36:37], v[48:49] op_sel_hi:[0,1]
	v_pk_fma_f32 v[4:5], v[24:25], v[4:5], v[42:43] op_sel_hi:[0,1,1]
	v_pk_fma_f32 v[0:1], v[28:29], v[52:53], v[0:1] op_sel_hi:[0,1,1]
	v_pk_fma_f32 v[46:47], v[24:25], v[6:7], v[46:47] op_sel_hi:[0,1,1]
	v_pk_fma_f32 v[4:5], v[26:27], v[6:7], v[4:5] op_sel_hi:[0,1,1]
	v_pk_add_f32 v[0:1], v[32:33], v[0:1] op_sel_hi:[0,1]
	v_pk_fma_f32 v[6:7], v[26:27], v[44:45], v[46:47] op_sel_hi:[0,1,1]
	v_pk_add_f32 v[4:5], v[16:17], v[4:5] op_sel_hi:[0,1]
	v_pk_add_f32 v[38:39], v[32:33], v[38:39] op_sel_hi:[0,1]
	v_pk_add_f32 v[6:7], v[16:17], v[6:7] op_sel_hi:[0,1]
	v_pk_mul_f32 v[4:5], v[0:1], v[4:5]
	v_add_u32_e32 v23, s85, v79
	v_mov_b32_e32 v0, v41
	v_mov_b32_e32 v1, v40
	v_pk_mul_f32 v[6:7], v[38:39], v[6:7]
	ds_write_b128 v23, v[0:3]
	ds_write_b128 v23, v[4:7] offset:16
	v_lshlrev_b32_e32 v1, 16, v80
	v_mul_f32_e32 v5, v78, v1
	v_lshlrev_b32_e32 v1, 16, v84
	v_lshlrev_b32_e32 v0, 16, v83
	v_mul_f32_e32 v6, v77, v1
	s_waitcnt vmcnt(1)
; #define LAS __attribute__((address_space(3)))
; __device__ __forceinline__ float bflo(unsigned w) { return __uint_as_float(w << 16); }
; __device__ __forceinline__ float bfhi(unsigned w) { return __uint_as_float(w & 0xffff0000u); }
; __device__ __forceinline__ float bf1(bf16 h) { return __uint_as_float((unsigned)h << 16); }
; __device__ __forceinline__ void conv8(const bf16* row, int p0, float c0, float c1, float c2, float cb, float (&o)[8]) {
;     const v4u w = *(const v4u*)(row + p0);
;     float x[10];
;     x[0] = bf1(row[p0 > 0 ? p0 - 1 : 0]) * (p0 > 0 ? 1.f : 0.f); x[9] = bf1(row[p0 + 8 < SEQL ? p0 + 8 : SEQL - 1]) * (p0 + 8 < SEQL ? 1.f : 0.f);
;     x[1] = bflo(w.x); x[2] = bfhi(w.x); x[3] = bflo(w.y); x[4] = bfhi(w.y); x[5] = bflo(w.z); x[6] = bfhi(w.z); x[7] = bflo(w.w); x[8] = bfhi(w.w);
; #pragma unroll
;     for (int e = 0; e < 8; ++e) o[e] = c0 * x[e] + c1 * x[e + 1] + c2 * x[e + 2] + cb;
; }
; template <int VAR> __device__ __forceinline__ void hyena_conv_phase(const Frame& F, const bf16* ZT, const bf16* GT, const float* conv_w, const float* conv_b, const float* skip, float* gscr, float* zscr, bf16* UT) {
;     ...
; #pragma unroll
;         for (int qi = 0; qi < 8; ++qi) { const int q = t + 512 * qi; const int b = qi >> 2, p0 = (q & 2047) * 8; float cv[8], cx[8];
;             conv8(rv + b * SEQL, p0, v0, v1, v2, vb, cv); conv8(rx1 + b * SEQL, p0, b0, b1, b2, bb, cx);
;             f32x4 o0, o1;
; #pragma unroll
;             for (int e = 0; e < 4; ++e) { o0[e] = cv[e] * cx[e]; o1[e] = cv[4 + e] * cx[4 + e]; }
;             *(LAS f32x4*)(X + b * SEQL + p0) = o0; *(LAS f32x4*)(X + b * SEQL + p0 + 4) = o1; }
;         __syncthreads();
;         { gv4* pz = (gv4*)zs + t; LAS const float* x0p = X + t; LAS const float* x1p = X + SEQL + t; asm volatile("" : "+v"(x0p), "+v"(x1p), "+v"(pz));
	v_mov_b32_e32 v8, v250
	v_mov_b32_e32 v9, v251
	v_mov_b32_e32 v10, v252
	v_mov_b32_e32 v11, v253
	v_lshlrev_b32_e32 v2, 16, v8
	v_and_b32_e32 v43, s0, v9
	v_and_b32_e32 v42, 0xffff0000, v8
	v_lshlrev_b32_e32 v3, 16, v9
	s_waitcnt vmcnt(0)
	v_and_b32_e32 v45, s0, v13
	v_and_b32_e32 v44, 0xffff0000, v12
	v_lshlrev_b32_e32 v23, 16, v13
	v_lshlrev_b32_e32 v1, 16, v81
	v_pk_mov_b32 v[42:43], v[2:3], v[42:43] op_sel:[1,0]
	v_pk_mov_b32 v[44:45], v[22:23], v[44:45] op_sel:[1,0]
	v_mul_f32_e32 v0, v77, v0
	v_mul_f32_e32 v39, v78, v1
	v_mov_b32_e32 v1, v43
	v_mov_b32_e32 v7, v45
	v_lshlrev_b32_e32 v40, 16, v12
	v_pk_mul_f32 v[0:1], v[30:31], v[0:1]
	v_pk_mul_f32 v[6:7], v[24:25], v[6:7]
	v_pk_fma_f32 v[0:1], v[30:31], v[2:3], v[0:1] op_sel:[0,0,1] op_sel_hi:[1,0,0]
	v_pk_fma_f32 v[6:7], v[24:25], v[40:41], v[6:7] op_sel:[0,0,1] op_sel_hi:[1,0,0]
	v_pk_fma_f32 v[0:1], v[28:29], v[42:43], v[0:1] op_sel_hi:[0,1,1]
	v_pk_fma_f32 v[6:7], v[26:27], v[44:45], v[6:7] op_sel_hi:[0,1,1]
	v_pk_add_f32 v[0:1], v[32:33], v[0:1] op_sel_hi:[0,1]
	v_pk_add_f32 v[6:7], v[16:17], v[6:7] op_sel_hi:[0,1]
	v_pk_mul_f32 v[40:41], v[0:1], v[6:7]
	v_and_b32_e32 v1, 16, v10
	v_and_b32_e32 v0, 0xffff0000, v9
	v_and_b32_e32 v47, 16, v14
	v_and_b32_e32 v46, 0xffff0000, v13
	v_mov_b32_e32 v6, v0
	v_pk_mul_f32 v[42:43], v[30:31], v[42:43] op_sel_hi:[0,1]
	v_pk_mul_f32 v[44:45], v[24:25], v[44:45] op_sel_hi:[0,1]
	v_pk_mov_b32 v[0:1], v[2:3], v[0:1] op_sel:[1,0]
	v_pk_mov_b32 v[2:3], v[22:23], v[46:47] op_sel:[1,0]
	v_lshlrev_b32_e32 v7, 16, v10
	v_lshlrev_b32_e32 v13, 16, v14
	v_mov_b32_e32 v12, v46
	v_pk_fma_f32 v[0:1], v[34:35], v[0:1], v[42:43] op_sel:[0,0,1] op_sel_hi:[0,1,0]
	v_pk_fma_f32 v[2:3], v[36:37], v[2:3], v[44:45] op_sel:[0,0,1] op_sel_hi:[0,1,0]
	v_and_b32_e32 v9, 16, v11
	v_and_b32_e32 v8, 0xffff0000, v10
	v_pk_fma_f32 v[0:1], v[28:29], v[6:7], v[0:1] op_sel_hi:[0,1,1]
	v_pk_fma_f32 v[2:3], v[26:27], v[12:13], v[2:3] op_sel_hi:[0,1,1]
	v_and_b32_e32 v4, 0xffff0000, v11
	v_lshlrev_b32_e32 v11, 16, v11
	v_mov_b32_e32 v10, v8
	v_pk_mov_b32 v[8:9], v[6:7], v[8:9] op_sel:[1,0]
	v_pk_add_f32 v[0:1], v[32:33], v[0:1] op_sel_hi:[0,1]
	v_pk_add_f32 v[2:3], v[16:17], v[2:3] op_sel_hi:[0,1]
	v_pk_mul_f32 v[2:3], v[0:1], v[2:3]
	v_mov_b32_e32 v0, v11
	v_mov_b32_e32 v1, v4
	v_pk_mul_f32 v[8:9], v[34:35], v[8:9] op_sel_hi:[0,1]
	v_and_b32_e32 v38, 0xffff0000, v15
	v_and_b32_e32 v49, 16, v15
	v_and_b32_e32 v48, 0xffff0000, v14
	v_lshlrev_b32_e32 v15, 16, v15
	v_pk_mul_f32 v[0:1], v[34:35], v[0:1] op_sel_hi:[0,1]
	v_pk_fma_f32 v[6:7], v[30:31], v[6:7], v[8:9] op_sel_hi:[0,1,1]
	v_mov_b32_e32 v14, v48
	v_pk_mov_b32 v[48:49], v[12:13], v[48:49] op_sel:[1,0]
	v_mov_b32_e32 v42, v15
	v_mov_b32_e32 v43, v38
	v_pk_fma_f32 v[0:1], v[30:31], v[10:11], v[0:1] op_sel_hi:[0,1,1]
	v_pk_fma_f32 v[6:7], v[28:29], v[10:11], v[6:7] op_sel_hi:[0,1,1]
	v_pk_fma_f32 v[0:1], v[28:29], v[4:5], v[0:1] op_sel_hi:[0,1,1]
	v_pk_add_f32 v[4:5], v[32:33], v[6:7] op_sel_hi:[0,1]
	v_pk_mul_f32 v[6:7], v[36:37], v[48:49] op_sel_hi:[0,1]
	v_pk_mul_f32 v[8:9], v[36:37], v[42:43] op_sel_hi:[0,1]
	v_pk_fma_f32 v[8:9], v[24:25], v[14:15], v[8:9] op_sel_hi:[0,1,1]
	v_pk_fma_f32 v[6:7], v[24:25], v[12:13], v[6:7] op_sel_hi:[0,1,1]
	v_pk_fma_f32 v[6:7], v[26:27], v[14:15], v[6:7] op_sel_hi:[0,1,1]
	v_pk_fma_f32 v[8:9], v[26:27], v[38:39], v[8:9] op_sel_hi:[0,1,1]
	v_pk_add_f32 v[0:1], v[32:33], v[0:1] op_sel_hi:[0,1]
	v_pk_add_f32 v[8:9], v[16:17], v[8:9] op_sel_hi:[0,1]
	v_pk_add_f32 v[6:7], v[16:17], v[6:7] op_sel_hi:[0,1]
	v_pk_mul_f32 v[4:5], v[4:5], v[6:7]
	v_pk_mul_f32 v[6:7], v[0:1], v[8:9]
	v_add_u32_e32 v8, s85, v29
	v_mov_b32_e32 v0, v41
	v_mov_b32_e32 v1, v40
	ds_write_b128 v8, v[0:3]
	ds_write_b128 v8, v[4:7] offset:16
	v_ashrrev_i32_e32 v23, 31, v22
	v_lshlrev_b32_e32 v0, 2, v22
	v_lshl_add_u64 v[4:5], v[22:23], 4, s[0:1]
	v_add_u32_e32 v10, 0, v0
	v_add_u32_e32 v11, s85, v0
	s_waitcnt lgkmcnt(0)
	s_barrier
; #define LAS __attribute__((address_space(3)))
; __device__ __forceinline__ unsigned pk2(float lo, float hi) { unsigned r; asm("v_cvt_pk_bf16_f32 %0, %1, %2" : "=v"(r) : "v"(lo), "v"(hi)); return r; }
; template <int VAR> __device__ __forceinline__ void hyena_conv_phase(const Frame& F, const bf16* ZT, const bf16* GT, const float* conv_w, const float* conv_b, const float* skip, float* gscr, float* zscr, bf16* UT) {
;     ...
;         { gv4* pz = (gv4*)zs + t; LAS const float* x0p = X + t; LAS const float* x1p = X + SEQL + t; asm volatile("" : "+v"(x0p), "+v"(x1p), "+v"(pz));
; #pragma unroll
;           for (int g = 0; g < 8; ++g) { v4u w; w.x = pk2(x0p[512 * (4 * g)], x1p[512 * (4 * g)]); w.y = pk2(x0p[512 * (4 * g + 1)], x1p[512 * (4 * g + 1)]); w.z = pk2(x0p[512 * (4 * g + 2)], x1p[512 * (4 * g + 2)]); w.w = pk2(x0p[512 * (4 * g + 3)], x1p[512 * (4 * g + 3)]);
;               *pz = w; pz += 512; asm volatile("" : "+v"(pz)); } }
;         __syncthreads();
	ds_read2st64_b32 v[0:1], v10 offset1:8
	ds_read2st64_b32 v[2:3], v11 offset1:8
	ds_read2st64_b32 v[6:7], v10 offset0:16 offset1:24
	ds_read2st64_b32 v[8:9], v11 offset0:16 offset1:24
	s_waitcnt lgkmcnt(2)
	v_cvt_pk_bf16_f32 v0, v0, v2
	v_cvt_pk_bf16_f32 v1, v1, v3
	s_waitcnt lgkmcnt(0)
	v_cvt_pk_bf16_f32 v2, v6, v8
	v_cvt_pk_bf16_f32 v3, v7, v9
	global_store_dwordx4 v[4:5], v[0:3], off
	v_lshl_add_u64 v[4:5], v[4:5], 0, s[26:27]
	ds_read2st64_b32 v[0:1], v10 offset0:32 offset1:40
	ds_read2st64_b32 v[2:3], v11 offset0:32 offset1:40
	ds_read2st64_b32 v[6:7], v10 offset0:48 offset1:56
	ds_read2st64_b32 v[8:9], v11 offset0:48 offset1:56
	s_waitcnt lgkmcnt(2)
	v_cvt_pk_bf16_f32 v0, v0, v2
	v_cvt_pk_bf16_f32 v1, v1, v3
	s_waitcnt lgkmcnt(0)
	v_cvt_pk_bf16_f32 v2, v6, v8
	v_cvt_pk_bf16_f32 v3, v7, v9
	global_store_dwordx4 v[4:5], v[0:3], off
	v_lshl_add_u64 v[4:5], v[4:5], 0, s[26:27]
	ds_read2st64_b32 v[0:1], v10 offset0:64 offset1:72
	ds_read2st64_b32 v[2:3], v11 offset0:64 offset1:72
	ds_read2st64_b32 v[6:7], v10 offset0:80 offset1:88
	ds_read2st64_b32 v[8:9], v11 offset0:80 offset1:88
	s_waitcnt lgkmcnt(2)
	v_cvt_pk_bf16_f32 v0, v0, v2
	v_cvt_pk_bf16_f32 v1, v1, v3
	s_waitcnt lgkmcnt(0)
	v_cvt_pk_bf16_f32 v2, v6, v8
	v_cvt_pk_bf16_f32 v3, v7, v9
	global_store_dwordx4 v[4:5], v[0:3], off
	v_lshl_add_u64 v[4:5], v[4:5], 0, s[26:27]
	ds_read2st64_b32 v[0:1], v10 offset0:96 offset1:104
	ds_read2st64_b32 v[2:3], v11 offset0:96 offset1:104
	ds_read2st64_b32 v[6:7], v10 offset0:112 offset1:120
	ds_read2st64_b32 v[8:9], v11 offset0:112 offset1:120
	s_waitcnt lgkmcnt(2)
	v_cvt_pk_bf16_f32 v0, v0, v2
	v_cvt_pk_bf16_f32 v1, v1, v3
	s_waitcnt lgkmcnt(0)
	v_cvt_pk_bf16_f32 v2, v6, v8
	v_cvt_pk_bf16_f32 v3, v7, v9
	global_store_dwordx4 v[4:5], v[0:3], off
	v_lshl_add_u64 v[4:5], v[4:5], 0, s[26:27]
	ds_read2st64_b32 v[0:1], v10 offset0:128 offset1:136
	ds_read2st64_b32 v[2:3], v11 offset0:128 offset1:136
	ds_read2st64_b32 v[6:7], v10 offset0:144 offset1:152
	ds_read2st64_b32 v[8:9], v11 offset0:144 offset1:152
	s_waitcnt lgkmcnt(2)
	v_cvt_pk_bf16_f32 v0, v0, v2
	v_cvt_pk_bf16_f32 v1, v1, v3
	s_waitcnt lgkmcnt(0)
	v_cvt_pk_bf16_f32 v2, v6, v8
	v_cvt_pk_bf16_f32 v3, v7, v9
	global_store_dwordx4 v[4:5], v[0:3], off
	v_lshl_add_u64 v[4:5], v[4:5], 0, s[26:27]
	ds_read2st64_b32 v[0:1], v10 offset0:160 offset1:168
	ds_read2st64_b32 v[2:3], v11 offset0:160 offset1:168
	ds_read2st64_b32 v[6:7], v10 offset0:176 offset1:184
	ds_read2st64_b32 v[8:9], v11 offset0:176 offset1:184
	s_waitcnt lgkmcnt(2)
	v_cvt_pk_bf16_f32 v0, v0, v2
	v_cvt_pk_bf16_f32 v1, v1, v3
	s_waitcnt lgkmcnt(0)
	v_cvt_pk_bf16_f32 v2, v6, v8
	v_cvt_pk_bf16_f32 v3, v7, v9
	global_store_dwordx4 v[4:5], v[0:3], off
	v_lshl_add_u64 v[4:5], v[4:5], 0, s[26:27]
	ds_read2st64_b32 v[0:1], v10 offset0:192 offset1:200
	ds_read2st64_b32 v[2:3], v11 offset0:192 offset1:200
	ds_read2st64_b32 v[6:7], v10 offset0:208 offset1:216
	ds_read2st64_b32 v[8:9], v11 offset0:208 offset1:216
	s_waitcnt lgkmcnt(2)
	v_cvt_pk_bf16_f32 v0, v0, v2
	v_cvt_pk_bf16_f32 v1, v1, v3
	s_waitcnt lgkmcnt(0)
	v_cvt_pk_bf16_f32 v2, v6, v8
	v_cvt_pk_bf16_f32 v3, v7, v9
	global_store_dwordx4 v[4:5], v[0:3], off
	v_lshl_add_u64 v[4:5], v[4:5], 0, s[26:27]
	ds_read2st64_b32 v[0:1], v10 offset0:224 offset1:232
	ds_read2st64_b32 v[2:3], v11 offset0:224 offset1:232
	ds_read2st64_b32 v[6:7], v10 offset0:240 offset1:248
	ds_read2st64_b32 v[8:9], v11 offset0:240 offset1:248
	s_waitcnt lgkmcnt(2)
	v_cvt_pk_bf16_f32 v0, v0, v2
	v_cvt_pk_bf16_f32 v1, v1, v3
	s_waitcnt lgkmcnt(0)
	v_cvt_pk_bf16_f32 v2, v6, v8
	v_cvt_pk_bf16_f32 v3, v7, v9
	global_store_dwordx4 v[4:5], v[0:3], off
	s_nop 1
	v_lshl_add_u64 v[0:1], v[4:5], 0, s[26:27]
	s_barrier
	s_branch .LBB0_325

; __device__ __forceinline__ unsigned pk2(float lo, float hi) { unsigned r; asm("v_cvt_pk_bf16_f32 %0, %1, %2" : "=v"(r) : "v"(lo), "v"(hi)); return r; }
; __device__ __forceinline__ float bf1(bf16 h) { return __uint_as_float((unsigned)h << 16); }
; template <int VAR> __device__ __forceinline__ void hyena_conv_phase(const Frame& F, const bf16* ZT, const bf16* GT, const float* conv_w, const float* conv_b, const float* skip, float* gscr, float* zscr, bf16* UT) {
;     ...
;             } else if (job == 0) { const bf16* pf = gf + t; const bf16* pb = gb + (SEQL - t); float asum = 0.f; float dprev = 0.f;
; #pragma unroll
;                 for (int n1 = 0; n1 < 32; ++n1) { const float f = bf1(*pf), bk = (n1 == 0 && t == 0) ? 0.f : bf1(*pb); pf += 512; pb -= 512; asm volatile("" : "+v"(pf), "+v"(pb));
;                     x[n1] = (f2){f + bk, 0.f}; asum += fabsf(f) + fabsf(bk);
;                     if (n1 & 1) dpk[n1 >> 1] = pk2(dprev, f - bk); else dprev = f - bk; }
.LBB0_331:
	s_andn2_b64 vcc, exec, s[6:7]
	v_ashrrev_i32_e32 v13, 31, v12
	s_cbranch_vccnz .LBB0_337
	v_lshl_add_u64 v[0:1], v[12:13], 1, s[90:91]
	global_load_ushort v4, v[0:1], off
	v_sub_u32_e32 v2, 0x4000, v12
	v_ashrrev_i32_e32 v3, 31, v2
	v_lshl_add_u64 v[2:3], v[2:3], 1, s[88:89]
	v_cmp_ne_u32_e32 vcc, 0, v12
	v_mov_b32_e32 v16, 0
	v_mov_b32_e32 v236, 0
	s_and_saveexec_b64 s[6:7], vcc
	s_cbranch_execz .LBB0_334
	global_load_ushort v236, v[2:3], off
.LBB0_334:
	s_or_b64 exec, exec, s[6:7]
	v_lshl_add_u64 v[0:1], v[0:1], 0, s[30:31]
	v_lshl_add_u64 v[2:3], v[2:3], 0, s[34:35]
	flat_load_ushort v5, v[2:3]
	flat_load_ushort v6, v[0:1]
	v_lshl_add_u64 v[0:1], v[0:1], 0, s[30:31]
	v_lshl_add_u64 v[2:3], v[2:3], 0, s[34:35]
	flat_load_ushort v7, v[2:3]
	flat_load_ushort v8, v[0:1]
	v_lshl_add_u64 v[0:1], v[0:1], 0, s[30:31]
	v_lshl_add_u64 v[2:3], v[2:3], 0, s[34:35]
	flat_load_ushort v9, v[2:3]
	flat_load_ushort v10, v[0:1]
	v_lshl_add_u64 v[0:1], v[0:1], 0, s[30:31]
	v_lshl_add_u64 v[2:3], v[2:3], 0, s[34:35]
	flat_load_ushort v11, v[2:3]
	flat_load_ushort v14, v[0:1]
	v_lshl_add_u64 v[0:1], v[0:1], 0, s[30:31]
	v_lshl_add_u64 v[2:3], v[2:3], 0, s[34:35]
	flat_load_ushort v15, v[2:3]
	flat_load_ushort v22, v[0:1]
	v_lshl_add_u64 v[0:1], v[0:1], 0, s[30:31]
	v_lshl_add_u64 v[2:3], v[2:3], 0, s[34:35]
	flat_load_ushort v23, v[2:3]
	flat_load_ushort v28, v[0:1]
	v_lshl_add_u64 v[0:1], v[0:1], 0, s[30:31]
	v_lshl_add_u64 v[2:3], v[2:3], 0, s[34:35]
	flat_load_ushort v29, v[2:3]
	flat_load_ushort v30, v[0:1]
	v_lshl_add_u64 v[0:1], v[0:1], 0, s[30:31]
	v_lshl_add_u64 v[2:3], v[2:3], 0, s[34:35]
	flat_load_ushort v31, v[2:3]
	flat_load_ushort v33, v[0:1]
	v_lshl_add_u64 v[0:1], v[0:1], 0, s[30:31]
	v_lshl_add_u64 v[2:3], v[2:3], 0, s[34:35]
	flat_load_ushort v34, v[2:3]
	flat_load_ushort v35, v[0:1]
	v_lshl_add_u64 v[0:1], v[0:1], 0, s[30:31]
	v_lshl_add_u64 v[2:3], v[2:3], 0, s[34:35]
	flat_load_ushort v36, v[0:1]
	flat_load_ushort v37, v[2:3]
	v_lshl_add_u64 v[0:1], v[0:1], 0, s[30:31]
	v_lshl_add_u64 v[2:3], v[2:3], 0, s[34:35]
	flat_load_ushort v42, v[0:1]
	flat_load_ushort v43, v[2:3]
	v_lshl_add_u64 v[0:1], v[0:1], 0, s[30:31]
	v_lshl_add_u64 v[2:3], v[2:3], 0, s[34:35]
	flat_load_ushort v44, v[0:1]
	flat_load_ushort v45, v[2:3]
	v_lshl_add_u64 v[0:1], v[0:1], 0, s[30:31]
	v_lshl_add_u64 v[2:3], v[2:3], 0, s[34:35]
	flat_load_ushort v46, v[0:1]
	flat_load_ushort v47, v[2:3]
	v_lshl_add_u64 v[0:1], v[0:1], 0, s[30:31]
	v_lshl_add_u64 v[2:3], v[2:3], 0, s[34:35]
	flat_load_ushort v48, v[0:1]
	flat_load_ushort v49, v[2:3]
	v_lshl_add_u64 v[24:25], v[0:1], 0, s[30:31]
	v_lshl_add_u64 v[26:27], v[2:3], 0, s[34:35]
	flat_load_ushort v50, v[24:25]
	flat_load_ushort v51, v[26:27]
	s_waitcnt vmcnt(0)
	v_lshlrev_b32_e32 v16, 16, v236
	v_lshlrev_b32_e32 v70, 16, v4
	v_add_f32_e64 v4, |v70|, |v16|
	v_sub_f32_e32 v32, v70, v16
	v_lshl_add_u64 v[38:39], v[24:25], 0, s[30:31]
	v_lshl_add_u64 v[40:41], v[26:27], 0, s[34:35]
	flat_load_ushort v52, v[40:41]
	v_lshl_add_u64 v[40:41], v[40:41], 0, s[34:35]
	s_waitcnt lgkmcnt(0)
	v_lshlrev_b32_e32 v1, 16, v5
	v_lshlrev_b32_e32 v0, 16, v6
	v_add_f32_e64 v2, |v0|, |v1|
	v_sub_f32_e32 v3, v0, v1
	v_add_f32_e32 v4, v4, v2
	v_cvt_pk_bf16_f32 v194, v32, v3
	v_lshlrev_b32_e32 v3, 16, v7
	v_lshlrev_b32_e32 v2, 16, v8
	v_add_f32_e64 v5, |v2|, |v3|
	v_add_f32_e32 v6, v4, v5
	v_lshlrev_b32_e32 v5, 16, v9
	v_lshlrev_b32_e32 v4, 16, v10
	v_add_f32_e64 v8, |v4|, |v5|
	v_sub_f32_e32 v7, v2, v3
	v_add_f32_e32 v8, v6, v8
	v_sub_f32_e32 v6, v4, v5
	v_cvt_pk_bf16_f32 v195, v7, v6
	v_lshlrev_b32_e32 v7, 16, v11
	v_lshlrev_b32_e32 v6, 16, v14
	v_add_f32_e64 v9, |v6|, |v7|
	v_add_f32_e32 v10, v8, v9
	v_lshlrev_b32_e32 v9, 16, v15
	v_lshlrev_b32_e32 v8, 16, v22
	v_add_f32_e64 v14, |v8|, |v9|
	v_sub_f32_e32 v11, v6, v7
	v_add_f32_e32 v14, v10, v14
	v_sub_f32_e32 v10, v8, v9
	v_cvt_pk_bf16_f32 v196, v11, v10
	v_lshlrev_b32_e32 v11, 16, v23
	v_lshlrev_b32_e32 v10, 16, v28
	v_add_f32_e64 v15, |v10|, |v11|
	v_add_f32_e32 v22, v14, v15
	v_lshlrev_b32_e32 v15, 16, v29
	v_lshlrev_b32_e32 v14, 16, v30
	v_add_f32_e64 v28, |v14|, |v15|
	v_sub_f32_e32 v23, v10, v11
	v_add_f32_e32 v28, v22, v28
	v_sub_f32_e32 v22, v14, v15
	v_cvt_pk_bf16_f32 v197, v23, v22
	v_lshlrev_b32_e32 v23, 16, v31
	v_lshlrev_b32_e32 v22, 16, v33
	v_add_f32_e64 v24, |v22|, |v23|
	v_add_f32_e32 v26, v28, v24
	v_lshlrev_b32_e32 v25, 16, v34
	v_lshlrev_b32_e32 v24, 16, v35
	v_add_f32_e64 v28, |v24|, |v25|
	v_sub_f32_e32 v27, v22, v23
	v_add_f32_e32 v28, v26, v28
	v_sub_f32_e32 v26, v24, v25
	v_cvt_pk_bf16_f32 v198, v27, v26
	v_lshlrev_b32_e32 v27, 16, v37
	v_lshlrev_b32_e32 v26, 16, v36
	v_add_f32_e64 v29, |v26|, |v27|
	v_add_f32_e32 v30, v28, v29
	v_lshlrev_b32_e32 v29, 16, v43
	v_lshlrev_b32_e32 v28, 16, v42
	v_add_f32_e64 v32, |v28|, |v29|
	v_sub_f32_e32 v31, v26, v27
	v_add_f32_e32 v32, v30, v32
	v_sub_f32_e32 v30, v28, v29
	v_cvt_pk_bf16_f32 v199, v31, v30
	v_lshlrev_b32_e32 v31, 16, v45
	v_lshlrev_b32_e32 v30, 16, v44
	flat_load_ushort v45, v[38:39]
	v_lshl_add_u64 v[38:39], v[38:39], 0, s[30:31]
	v_add_f32_e64 v33, |v30|, |v31|
	v_add_f32_e32 v34, v32, v33
	v_lshlrev_b32_e32 v33, 16, v47
	v_lshlrev_b32_e32 v32, 16, v46
	flat_load_ushort v46, v[40:41]
	flat_load_ushort v47, v[38:39]
	v_add_f32_e64 v36, |v32|, |v33|
	v_lshl_add_u64 v[38:39], v[38:39], 0, s[30:31]
	v_lshl_add_u64 v[40:41], v[40:41], 0, s[34:35]
	v_sub_f32_e32 v35, v30, v31
	v_add_f32_e32 v36, v34, v36
	v_sub_f32_e32 v34, v32, v33
	v_cvt_pk_bf16_f32 v200, v35, v34
	v_lshlrev_b32_e32 v35, 16, v49
	v_lshlrev_b32_e32 v34, 16, v48
	flat_load_ushort v48, v[40:41]
	flat_load_ushort v49, v[38:39]
; __device__ __forceinline__ unsigned pk2(float lo, float hi) { unsigned r; asm("v_cvt_pk_bf16_f32 %0, %1, %2" : "=v"(r) : "v"(lo), "v"(hi)); return r; }
; __device__ __forceinline__ float bf1(bf16 h) { return __uint_as_float((unsigned)h << 16); }
; __device__ __forceinline__ float rdl(float v, int l) { return __int_as_float(__builtin_amdgcn_readlane(__float_as_int(v), l)); }
; __device__ __forceinline__ float lx1(float v) { return __int_as_float(__builtin_amdgcn_update_dpp(0, __float_as_int(v), 0xB1, 0xF, 0xF, true)); }
; __device__ __forceinline__ float lx2(float v) { return __int_as_float(__builtin_amdgcn_update_dpp(0, __float_as_int(v), 0x4E, 0xF, 0xF, true)); }
; __device__ __forceinline__ float lx4(float v) { return __int_as_float(__builtin_amdgcn_ds_swizzle(__float_as_int(v), 0x101F)); }
; __device__ __forceinline__ float lx8(float v) { return __int_as_float(__builtin_amdgcn_update_dpp(0, __float_as_int(v), 0x128, 0xF, 0xF, true)); }
; template <int VAR> __device__ __forceinline__ void hyena_conv_phase(const Frame& F, const bf16* ZT, const bf16* GT, const float* conv_w, const float* conv_b, const float* skip, float* gscr, float* zscr, bf16* UT) {
;     ...
;             } else if (job == 0) { const bf16* pf = gf + t; const bf16* pb = gb + (SEQL - t); float asum = 0.f; float dprev = 0.f;
; #pragma unroll
;                 for (int n1 = 0; n1 < 32; ++n1) { const float f = bf1(*pf), bk = (n1 == 0 && t == 0) ? 0.f : bf1(*pb); pf += 512; pb -= 512; asm volatile("" : "+v"(pf), "+v"(pb));
;                     x[n1] = (f2){f + bk, 0.f}; asum += fabsf(f) + fabsf(bk);
;                     if (n1 & 1) dpk[n1 >> 1] = pk2(dprev, f - bk); else dprev = f - bk; }
;                 {
;                     float v = asum; v += lx1(v); v += lx2(v); v += lx4(v); v += lx8(v);
;                     v += __int_as_float(__builtin_amdgcn_ds_swizzle(__float_as_int(v), 0x401F));
;                     const float w64 = rdl(v, 0) + rdl(v, 32);
;                     if (F.lane == 0) RED[F.wave] = w64;
;                     __syncthreads();
	v_lshl_add_u64 v[38:39], v[38:39], 0, s[30:31]
	v_lshl_add_u64 v[40:41], v[40:41], 0, s[34:35]
	v_add_f32_e64 v37, |v34|, |v35|
	v_add_f32_e32 v42, v36, v37
	v_lshlrev_b32_e32 v37, 16, v51
	v_lshlrev_b32_e32 v36, 16, v50
	flat_load_ushort v50, v[40:41]
	flat_load_ushort v51, v[38:39]
	v_lshl_add_u64 v[38:39], v[38:39], 0, s[30:31]
	v_lshl_add_u64 v[40:41], v[40:41], 0, s[34:35]
	flat_load_ushort v53, v[40:41]
	flat_load_ushort v54, v[38:39]
	v_lshl_add_u64 v[38:39], v[38:39], 0, s[30:31]
	v_lshl_add_u64 v[40:41], v[40:41], 0, s[34:35]
	flat_load_ushort v55, v[40:41]
	flat_load_ushort v56, v[38:39]
	v_add_f32_e64 v44, |v36|, |v37|
	v_lshl_add_u64 v[38:39], v[38:39], 0, s[30:31]
	v_lshl_add_u64 v[40:41], v[40:41], 0, s[34:35]
	v_sub_f32_e32 v43, v34, v35
	v_add_f32_e32 v44, v42, v44
	v_sub_f32_e32 v42, v36, v37
	v_cvt_pk_bf16_f32 v201, v43, v42
	flat_load_ushort v57, v[40:41]
	flat_load_ushort v58, v[38:39]
	v_lshl_add_u64 v[42:43], v[38:39], 0, s[30:31]
	v_lshl_add_u64 v[40:41], v[40:41], 0, s[34:35]
	flat_load_ushort v59, v[40:41]
	flat_load_ushort v60, v[42:43]
	v_lshl_add_u64 v[42:43], v[42:43], 0, s[30:31]
	v_lshl_add_u64 v[40:41], v[40:41], 0, s[34:35]
	flat_load_ushort v61, v[40:41]
	flat_load_ushort v62, v[42:43]
	v_lshl_add_u64 v[42:43], v[42:43], 0, s[30:31]
	v_lshl_add_u64 v[40:41], v[40:41], 0, s[34:35]
	flat_load_ushort v63, v[40:41]
	flat_load_ushort v64, v[42:43]
	v_lshl_add_u64 v[42:43], v[42:43], 0, s[30:31]
	v_lshl_add_u64 v[40:41], v[40:41], 0, s[34:35]
	flat_load_ushort v65, v[42:43]
	flat_load_ushort v66, v[40:41]
	v_lshl_add_u64 v[42:43], v[42:43], 0, s[30:31]
	v_lshl_add_u64 v[40:41], v[40:41], 0, s[34:35]
	flat_load_ushort v67, v[42:43]
	flat_load_ushort v68, v[40:41]
	v_lshl_add_u64 v[42:43], v[42:43], 0, s[30:31]
	v_lshl_add_u64 v[40:41], v[40:41], 0, s[34:35]
	flat_load_ushort v69, v[42:43]
	flat_load_ushort v71, v[40:41]
	v_lshl_add_u64 v[42:43], v[42:43], 0, s[30:31]
	v_lshl_add_u64 v[40:41], v[40:41], 0, s[34:35]
	flat_load_ushort v76, v[42:43]
	flat_load_ushort v77, v[40:41]
	v_lshl_add_u64 v[42:43], v[42:43], 0, s[30:31]
	v_lshl_add_u64 v[40:41], v[40:41], 0, s[34:35]
	flat_load_ushort v78, v[42:43]
	flat_load_ushort v79, v[40:41]
	v_lshl_add_u64 v[72:73], v[42:43], 0, s[30:31]
	v_lshl_add_u64 v[74:75], v[40:41], 0, s[34:35]
	flat_load_ushort v80, v[74:75]
	flat_load_ushort v81, v[72:73]
	s_waitcnt vmcnt(0)
	v_lshlrev_b32_e32 v39, 16, v52
	s_waitcnt lgkmcnt(0)
	v_lshlrev_b32_e32 v38, 16, v45
	v_add_f32_e64 v40, |v38|, |v39|
	v_add_f32_e32 v42, v44, v40
	v_sub_f32_e32 v43, v38, v39
	v_lshl_add_u64 v[72:73], v[72:73], 0, s[30:31]
	v_lshlrev_b32_e32 v41, 16, v46
	v_lshlrev_b32_e32 v40, 16, v47
	v_add_f32_e64 v44, |v40|, |v41|
	v_add_f32_e32 v44, v42, v44
	v_sub_f32_e32 v42, v40, v41
	v_cvt_pk_bf16_f32 v202, v43, v42
	v_lshl_add_u64 v[74:75], v[74:75], 0, s[34:35]
	v_lshlrev_b32_e32 v43, 16, v48
	v_lshlrev_b32_e32 v42, 16, v49
	v_add_f32_e64 v45, |v42|, |v43|
	v_add_f32_e32 v46, v44, v45
	v_sub_f32_e32 v47, v42, v43
	v_lshlrev_b32_e32 v45, 16, v50
	v_lshlrev_b32_e32 v44, 16, v51
	v_add_f32_e64 v48, |v44|, |v45|
	v_add_f32_e32 v48, v46, v48
	v_sub_f32_e32 v46, v44, v45
	v_cvt_pk_bf16_f32 v203, v47, v46
	v_lshlrev_b32_e32 v47, 16, v53
	v_lshlrev_b32_e32 v46, 16, v54
	v_add_f32_e64 v49, |v46|, |v47|
	v_add_f32_e32 v50, v48, v49
	v_lshlrev_b32_e32 v49, 16, v55
	v_lshlrev_b32_e32 v48, 16, v56
	v_add_f32_e64 v52, |v48|, |v49|
	v_sub_f32_e32 v51, v46, v47
	v_add_f32_e32 v52, v50, v52
	v_sub_f32_e32 v50, v48, v49
	v_cvt_pk_bf16_f32 v204, v51, v50
	v_lshlrev_b32_e32 v51, 16, v57
	v_lshlrev_b32_e32 v50, 16, v58
	v_add_f32_e64 v53, |v50|, |v51|
	v_add_f32_e32 v54, v52, v53
	v_lshlrev_b32_e32 v53, 16, v59
	v_lshlrev_b32_e32 v52, 16, v60
	v_add_f32_e64 v56, |v52|, |v53|
	v_sub_f32_e32 v55, v50, v51
	v_add_f32_e32 v56, v54, v56
	v_sub_f32_e32 v54, v52, v53
	v_cvt_pk_bf16_f32 v205, v55, v54
	v_lshlrev_b32_e32 v55, 16, v61
	v_lshlrev_b32_e32 v54, 16, v62
	v_add_f32_e64 v57, |v54|, |v55|
	v_add_f32_e32 v58, v56, v57
	v_lshlrev_b32_e32 v57, 16, v63
	v_lshlrev_b32_e32 v56, 16, v64
	v_add_f32_e64 v60, |v56|, |v57|
	v_sub_f32_e32 v59, v54, v55
	v_add_f32_e32 v60, v58, v60
	v_sub_f32_e32 v58, v56, v57
	v_cvt_pk_bf16_f32 v206, v59, v58
	v_lshlrev_b32_e32 v59, 16, v66
	v_lshlrev_b32_e32 v58, 16, v65
	v_add_f32_e64 v61, |v58|, |v59|
	v_add_f32_e32 v62, v60, v61
	v_lshlrev_b32_e32 v61, 16, v68
	v_lshlrev_b32_e32 v60, 16, v67
	v_add_f32_e64 v64, |v60|, |v61|
	v_sub_f32_e32 v63, v58, v59
	v_add_f32_e32 v64, v62, v64
	v_sub_f32_e32 v62, v60, v61
	v_cvt_pk_bf16_f32 v207, v63, v62
	v_lshlrev_b32_e32 v63, 16, v71
	v_lshlrev_b32_e32 v62, 16, v69
	v_add_f32_e64 v65, |v62|, |v63|
	v_add_f32_e32 v66, v64, v65
	v_lshlrev_b32_e32 v65, 16, v77
	v_lshlrev_b32_e32 v64, 16, v76
	v_add_f32_e64 v67, |v64|, |v65|
	v_add_f32_e32 v68, v66, v67
	v_lshlrev_b32_e32 v67, 16, v79
	v_lshlrev_b32_e32 v66, 16, v78
	v_add_f32_e64 v69, |v66|, |v67|
	v_add_f32_e32 v76, v68, v69
	v_lshlrev_b32_e32 v69, 16, v80
	v_lshlrev_b32_e32 v68, 16, v81
	v_add_f32_e64 v77, |v68|, |v69|
	v_add_f32_e32 v76, v76, v77
	v_sub_f32_e32 v71, v62, v63
	v_sub_f32_e32 v78, v64, v65
	v_add_f32_dpp v76, v76, v76 quad_perm:[1,0,3,2] row_mask:0xf bank_mask:0xf bound_ctrl:1
	v_cvt_pk_bf16_f32 v208, v71, v78
	v_sub_f32_e32 v71, v66, v67
	v_sub_f32_e32 v72, v68, v69
	v_add_f32_dpp v76, v76, v76 quad_perm:[2,3,0,1] row_mask:0xf bank_mask:0xf bound_ctrl:1
	ds_swizzle_b32 v77, v76 offset:swizzle(SWAP,4)
	v_cvt_pk_bf16_f32 v209, v71, v72
	s_waitcnt lgkmcnt(0)
	v_add_f32_e32 v76, v76, v77
	s_nop 1
	v_add_f32_dpp v76, v76, v76 row_ror:8 row_mask:0xf bank_mask:0xf bound_ctrl:1
	ds_swizzle_b32 v77, v76 offset:swizzle(SWAP,16)
	s_waitcnt lgkmcnt(0)
	v_add_f32_e32 v71, v76, v77
	s_nop 0
	v_readlane_b32 s20, v71, 0
	v_readlane_b32 s21, v71, 32
	s_and_saveexec_b64 s[6:7], s[4:5]
	s_nop 0
	v_mov_b32_e32 v71, s21
	v_add_f32_e32 v71, s20, v71
	v_mov_b32_e32 v72, s3
	ds_write_b32 v72, v71
	s_or_b64 exec, exec, s[6:7]
	v_mov_b32_e32 v130, v67
	v_pk_add_f32 v[66:67], v[130:131], v[66:67]
	s_add_i32 s6, 0, 0x22300
	v_mov_b32_e32 v72, v1
	v_mov_b32_e32 v74, v3
	v_mov_b32_e32 v76, v5
	v_mov_b32_e32 v78, v7
	v_mov_b32_e32 v67, s6
	v_pk_add_f32 v[0:1], v[72:73], v[0:1]
	v_pk_add_f32 v[2:3], v[74:75], v[2:3]
	v_pk_add_f32 v[4:5], v[76:77], v[4:5]
	v_pk_add_f32 v[6:7], v[78:79], v[6:7]
	s_waitcnt lgkmcnt(0)
	s_barrier
; __device__ __forceinline__ unsigned pk2(float lo, float hi) { unsigned r; asm("v_cvt_pk_bf16_f32 %0, %1, %2" : "=v"(r) : "v"(lo), "v"(hi)); return r; }
; __device__ __forceinline__ float rdl(float v, int l) { return __int_as_float(__builtin_amdgcn_readlane(__float_as_int(v), l)); }
; __device__ __forceinline__ float lx1(float v) { return __int_as_float(__builtin_amdgcn_update_dpp(0, __float_as_int(v), 0xB1, 0xF, 0xF, true)); }
; __device__ __forceinline__ float lx2(float v) { return __int_as_float(__builtin_amdgcn_update_dpp(0, __float_as_int(v), 0x4E, 0xF, 0xF, true)); }
; __device__ __forceinline__ float lx4(float v) { return __int_as_float(__builtin_amdgcn_ds_swizzle(__float_as_int(v), 0x101F)); }
; __device__ __forceinline__ float lx8(float v) { return __int_as_float(__builtin_amdgcn_update_dpp(0, __float_as_int(v), 0x128, 0xF, 0xF, true)); }
; template <int VAR> __device__ __forceinline__ void hyena_conv_phase(const Frame& F, const bf16* ZT, const bf16* GT, const float* conv_w, const float* conv_b, const float* skip, float* gscr, float* zscr, bf16* UT) {
;     ...
;                     x[n1] = (f2){f + bk, 0.f}; asum += fabsf(f) + fabsf(bk);
;                     if (n1 & 1) dpk[n1 >> 1] = pk2(dprev, f - bk); else dprev = f - bk; }
;                 {
;                     float v = asum; v += lx1(v); v += lx2(v); v += lx4(v); v += lx8(v);
;                     v += __int_as_float(__builtin_amdgcn_ds_swizzle(__float_as_int(v), 0x401F));
;                     const float w64 = rdl(v, 0) + rdl(v, 32);
;                     if (F.lane == 0) RED[F.wave] = w64;
;                     __syncthreads();
;                     const float tot = ((RED[0] + RED[1]) + (RED[2] + RED[3])) + ((RED[4] + RED[5]) + (RED[6] + RED[7]));
;                     __syncthreads();
;                     gsc = 1.0f / (tot * 32768.0f); }
	ds_read_b128 v[72:75], v67
	ds_read_b128 v[76:79], v67 offset:16
	v_mov_b32_e32 v132, v69
	v_add_f32_e32 v16, v16, v70
	v_pk_add_f32 v[70:71], v[132:133], v[68:69]
	s_waitcnt lgkmcnt(1)
	v_mov_b32_e32 v68, v72
	s_waitcnt lgkmcnt(0)
	v_mov_b32_e32 v69, v76
	v_mov_b32_e32 v76, v73
	v_mov_b32_e32 v72, v74
	v_mov_b32_e32 v73, v78
	v_mov_b32_e32 v78, v75
	v_pk_add_f32 v[68:69], v[68:69], v[76:77]
	v_pk_add_f32 v[72:73], v[72:73], v[78:79]
	v_mov_b32_e32 v80, v9
	v_pk_add_f32 v[68:69], v[68:69], v[72:73]
	v_mov_b32_e32 v82, v11
	v_add_f32_e32 v68, v68, v69
	v_mul_f32_e32 v68, 0x47000000, v68
	v_div_scale_f32 v69, s[6:7], v68, v68, 1.0
	v_rcp_f32_e32 v72, v69
	v_mov_b32_e32 v84, v15
	v_mov_b32_e32 v86, v23
	v_mov_b32_e32 v88, v25
	v_fma_f32 v73, -v69, v72, 1.0
	v_fmac_f32_e32 v72, v73, v72
	v_div_scale_f32 v73, vcc, 1.0, v68, 1.0
	v_mul_f32_e32 v74, v73, v72
	v_fma_f32 v75, -v69, v74, v73
	v_fmac_f32_e32 v74, v75, v72
	v_mov_b32_e32 v90, v27
	v_mov_b32_e32 v92, v29
	v_mov_b32_e32 v94, v31
	v_mov_b32_e32 v96, v33
	v_mov_b32_e32 v98, v35
	v_mov_b32_e32 v100, v37
	v_mov_b32_e32 v102, v39
	v_mov_b32_e32 v104, v41
	v_mov_b32_e32 v106, v43
	v_mov_b32_e32 v108, v45
	v_mov_b32_e32 v110, v47
	v_mov_b32_e32 v112, v49
	v_mov_b32_e32 v114, v51
	v_mov_b32_e32 v116, v53
	v_mov_b32_e32 v118, v55
	v_mov_b32_e32 v120, v57
	v_mov_b32_e32 v122, v59
	v_mov_b32_e32 v124, v61
	v_mov_b32_e32 v126, v63
	v_mov_b32_e32 v128, v65
	v_fma_f32 v69, -v69, v74, v73
	v_pk_add_f32 v[8:9], v[80:81], v[8:9]
	v_pk_add_f32 v[10:11], v[82:83], v[10:11]
	v_pk_add_f32 v[14:15], v[84:85], v[14:15]
	v_pk_add_f32 v[22:23], v[86:87], v[22:23]
	v_pk_add_f32 v[24:25], v[88:89], v[24:25]
	v_pk_add_f32 v[26:27], v[90:91], v[26:27]
	v_pk_add_f32 v[28:29], v[92:93], v[28:29]
	v_pk_add_f32 v[30:31], v[94:95], v[30:31]
	v_pk_add_f32 v[32:33], v[96:97], v[32:33]
	v_pk_add_f32 v[34:35], v[98:99], v[34:35]
	v_pk_add_f32 v[36:37], v[100:101], v[36:37]
	v_pk_add_f32 v[38:39], v[102:103], v[38:39]
	v_pk_add_f32 v[40:41], v[104:105], v[40:41]
	v_pk_add_f32 v[42:43], v[106:107], v[42:43]
	v_pk_add_f32 v[44:45], v[108:109], v[44:45]
	v_pk_add_f32 v[46:47], v[110:111], v[46:47]
	v_pk_add_f32 v[48:49], v[112:113], v[48:49]
	v_pk_add_f32 v[50:51], v[114:115], v[50:51]
	v_pk_add_f32 v[52:53], v[116:117], v[52:53]
	v_pk_add_f32 v[54:55], v[118:119], v[54:55]
	v_pk_add_f32 v[56:57], v[120:121], v[56:57]
	v_pk_add_f32 v[58:59], v[122:123], v[58:59]
	v_pk_add_f32 v[60:61], v[124:125], v[60:61]
	v_pk_add_f32 v[62:63], v[126:127], v[62:63]
	v_pk_add_f32 v[64:65], v[128:129], v[64:65]
	v_div_fmas_f32 v69, v69, v72, v74
	v_mov_b32_e32 v1, v17
	v_mov_b32_e32 v3, v17
	v_mov_b32_e32 v5, v17
	v_mov_b32_e32 v7, v17
	v_mov_b32_e32 v9, v17
	v_mov_b32_e32 v11, v17
	v_mov_b32_e32 v15, v17
	v_mov_b32_e32 v23, v17
	v_mov_b32_e32 v25, v17
	v_mov_b32_e32 v27, v17
	v_mov_b32_e32 v29, v17
	v_mov_b32_e32 v31, v17
	v_mov_b32_e32 v33, v17
	v_mov_b32_e32 v35, v17
	v_mov_b32_e32 v37, v17
	v_mov_b32_e32 v39, v17
	v_mov_b32_e32 v41, v17
	v_mov_b32_e32 v43, v17
	v_mov_b32_e32 v45, v17
	v_mov_b32_e32 v47, v17
	v_mov_b32_e32 v49, v17
	v_mov_b32_e32 v51, v17
	v_mov_b32_e32 v53, v17
	v_mov_b32_e32 v55, v17
	v_mov_b32_e32 v57, v17
	v_mov_b32_e32 v59, v17
	v_mov_b32_e32 v61, v17
	v_mov_b32_e32 v63, v17
	v_mov_b32_e32 v65, v17
	v_mov_b32_e32 v67, v17
	v_mov_b32_e32 v71, v17
	v_div_fixup_f32 v210, v69, v68, 1.0
	v_mov_b64_e32 v[68:69], v[16:17]
	s_barrier

; #define LAS __attribute__((address_space(3)))
; __global__ void __launch_bounds__(512) fwd_kernel(Args args) {
;     extern __shared__ __attribute__((aligned(16))) unsigned char lds_raw[];
;     Frame F; F.lds = (LAS unsigned char*)lds_raw; F.tid = threadIdx.x; F.lane = F.tid & 63; F.wave = __builtin_amdgcn_readfirstlane(F.tid >> 6); F.G = gridDim.x; F.bid = blockIdx.x;
;     cg::grid_group grid = cg::this_grid();
;     volatile LAS unsigned* BST = (volatile LAS unsigned*)(F.lds + LDS_BYTES - 64);
;     if (F.tid < 2) BST[F.tid] = 0u;
;     __syncthreads();
;     XcdBarrier xbar; xbar.bar = (unsigned*)(args.ws + WS_BAR); xbar.x = 0; xbar.st = BST;
	.amdhsa_kernel _Z10fwd_kernel4Args
		.amdhsa_group_segment_fixed_size 0
		.amdhsa_private_segment_fixed_size 0
		.amdhsa_kernarg_size 504
		.amdhsa_user_sgpr_count 2
		.amdhsa_user_sgpr_dispatch_ptr 0
		.amdhsa_user_sgpr_queue_ptr 0
		.amdhsa_user_sgpr_kernarg_segment_ptr 1
		.amdhsa_user_sgpr_dispatch_id 0
		.amdhsa_user_sgpr_kernarg_preload_length 0
		.amdhsa_user_sgpr_kernarg_preload_offset 0
		.amdhsa_user_sgpr_private_segment_size 0
		.amdhsa_uses_dynamic_stack 0
		.amdhsa_enable_private_segment 0
		.amdhsa_system_sgpr_workgroup_id_x 1
		.amdhsa_system_sgpr_workgroup_id_y 0
		.amdhsa_system_sgpr_workgroup_id_z 0
		.amdhsa_system_sgpr_workgroup_info 0
		.amdhsa_system_vgpr_workitem_id 2
		.amdhsa_next_free_vgpr 256
		.amdhsa_next_free_sgpr 100
		.amdhsa_accum_offset 256
		.amdhsa_reserve_vcc 1
		.amdhsa_float_round_mode_32 0
		.amdhsa_float_round_mode_16_64 0
		.amdhsa_float_denorm_mode_32 3
		.amdhsa_float_denorm_mode_16_64 3
		.amdhsa_dx10_clamp 1
		.amdhsa_ieee_mode 1
		.amdhsa_fp16_overflow 0
		.amdhsa_tg_split 0
		.amdhsa_exception_fp_ieee_invalid_op 0
		.amdhsa_exception_fp_denorm_src 0
		.amdhsa_exception_fp_ieee_div_zero 0
		.amdhsa_exception_fp_ieee_overflow 0
		.amdhsa_exception_fp_ieee_underflow 0
		.amdhsa_exception_fp_ieee_inexact 0
		.amdhsa_exception_int_div_zero 0
	.end_amdhsa_kernel

; #define LAS __attribute__((address_space(3)))
; __global__ void __launch_bounds__(512) fwd_kernel(Args args) {
;     extern __shared__ __attribute__((aligned(16))) unsigned char lds_raw[];
;     Frame F; F.lds = (LAS unsigned char*)lds_raw; F.tid = threadIdx.x; F.lane = F.tid & 63; F.wave = __builtin_amdgcn_readfirstlane(F.tid >> 6); F.G = gridDim.x; F.bid = blockIdx.x;
;     cg::grid_group grid = cg::this_grid();
;     volatile LAS unsigned* BST = (volatile LAS unsigned*)(F.lds + LDS_BYTES - 64);
;     if (F.tid < 2) BST[F.tid] = 0u;
;     __syncthreads();
;     XcdBarrier xbar; xbar.bar = (unsigned*)(args.ws + WS_BAR); xbar.x = 0; xbar.st = BST;
amdhsa.kernels:
  - .agpr_count:     0
    .args:
      - .offset:         0
        .size:           248
        .value_kind:     by_value
      - .offset:         248
        .size:           4
        .value_kind:     hidden_block_count_x
      - .offset:         252
        .size:           4
        .value_kind:     hidden_block_count_y
      - .offset:         256
        .size:           4
        .value_kind:     hidden_block_count_z
      - .offset:         260
        .size:           2
        .value_kind:     hidden_group_size_x
      - .offset:         262
        .size:           2
        .value_kind:     hidden_group_size_y
      - .offset:         264
        .size:           2
        .value_kind:     hidden_group_size_z
      - .offset:         266
        .size:           2
        .value_kind:     hidden_remainder_x
      - .offset:         268
        .size:           2
        .value_kind:     hidden_remainder_y
      - .offset:         270
        .size:           2
        .value_kind:     hidden_remainder_z
      - .offset:         288
        .size:           8
        .value_kind:     hidden_global_offset_x
      - .offset:         296
        .size:           8
        .value_kind:     hidden_global_offset_y
      - .offset:         304
        .size:           8
        .value_kind:     hidden_global_offset_z
      - .offset:         312
        .size:           2
        .value_kind:     hidden_grid_dims
      - .offset:         336
        .size:           8
        .value_kind:     hidden_multigrid_sync_arg
      - .offset:         368
        .size:           4
        .value_kind:     hidden_dynamic_lds_size
    .group_segment_fixed_size: 0
    .kernarg_segment_align: 8
    .kernarg_segment_size: 504
    .language:       OpenCL C
    .language_version:
      - 2
      - 0
    .max_flat_workgroup_size: 512
    .name:           _Z10fwd_kernel4Args
    .private_segment_fixed_size: 0
    .sgpr_count:     106
    .sgpr_spill_count: 22
    .symbol:         _Z10fwd_kernel4Args.kd
    .uniform_work_group_size: 1
    .uses_dynamic_stack: false
    .vgpr_count:     256
    .vgpr_spill_count: 0
    .wavefront_size: 64
